# nv + saddr-form LDS-DMA (no address VALU) in the other six GEMM K-loops
# speedup vs baseline: 1.0089x; 1.0023x over previous
.LBB0_256:
	v_add_u32_e32 v172, s70, v160
	v_add_u32_e32 v188, s71, v160
	ds_read_b128 v[154:157], v172
	ds_read_b128 v[164:167], v172 offset:1024
	ds_read_b128 v[168:171], v172 offset:2048
	ds_read_b128 v[172:175], v172 offset:3072
	ds_read_b128 v[176:179], v188
	ds_read_b128 v[180:183], v188 offset:1024
	ds_read_b128 v[184:187], v188 offset:2048
	ds_read_b128 v[188:191], v188 offset:3072
	s_add_i32 s75, s30, 2
	s_add_u32 s31, s28, 0xfffc0080
	s_addc_u32 s34, s29, -1
	s_cmp_eq_u32 s67, s30
	s_cselect_b32 s30, s26, s17
	s_cselect_b32 s35, s25, s34
	s_cselect_b32 s34, s24, s31
	s_cselect_b32 s31, s27, s19
	s_add_i32 m0, s58, 0xc000
	ds_read_b128 v[192:195], v163
	ds_read_b128 v[196:199], v163 offset:1024
	ds_read_b128 v[200:203], v163 offset:2048
	ds_read_b128 v[204:207], v163 offset:3072
	ds_read_b128 v[208:211], v163 offset:4096
	ds_read_b128 v[212:215], v163 offset:5120
	ds_read_b128 v[216:219], v163 offset:6144
	ds_read_b128 v[220:223], v163 offset:7168
	global_load_lds_dwordx4 v146, s[28:29]
	s_add_i32 m0, s58, 0xe000
	s_nop 0
	global_load_lds_dwordx4 v148, s[28:29]
	s_waitcnt vmcnt(8)
	s_waitcnt lgkmcnt(0)
	s_barrier
	v_mfma_f32_16x16x32_bf16 v[42:45], v[154:157], v[192:195], v[42:45]
	v_mfma_f32_16x16x32_bf16 v[42:45], v[164:167], v[196:199], v[42:45]
	v_mfma_f32_16x16x32_bf16 v[54:57], v[164:167], v[204:207], v[54:57]
	v_mfma_f32_16x16x32_bf16 v[54:57], v[154:157], v[200:203], v[54:57]
	v_mfma_f32_16x16x32_bf16 v[66:69], v[154:157], v[208:211], v[66:69]
	v_mfma_f32_16x16x32_bf16 v[66:69], v[164:167], v[212:215], v[66:69]
	v_mfma_f32_16x16x32_bf16 v[62:65], v[164:167], v[220:223], v[62:65]
	v_mfma_f32_16x16x32_bf16 v[62:65], v[154:157], v[216:219], v[62:65]
	v_mfma_f32_16x16x32_bf16 v[46:49], v[168:171], v[216:219], v[46:49]
	v_mfma_f32_16x16x32_bf16 v[46:49], v[172:175], v[220:223], v[46:49]
	v_mfma_f32_16x16x32_bf16 v[50:53], v[172:175], v[212:215], v[50:53]
	v_mfma_f32_16x16x32_bf16 v[50:53], v[168:171], v[208:211], v[50:53]
	v_mfma_f32_16x16x32_bf16 v[38:41], v[168:171], v[200:203], v[38:41]
	v_mfma_f32_16x16x32_bf16 v[38:41], v[172:175], v[204:207], v[38:41]
	v_mfma_f32_16x16x32_bf16 v[26:29], v[172:175], v[196:199], v[26:29]
	v_mfma_f32_16x16x32_bf16 v[26:29], v[168:171], v[192:195], v[26:29]
	v_mfma_f32_16x16x32_bf16 v[14:17], v[176:179], v[192:195], v[14:17]
	v_mfma_f32_16x16x32_bf16 v[14:17], v[180:183], v[196:199], v[14:17]
	v_mfma_f32_16x16x32_bf16 v[22:25], v[180:183], v[204:207], v[22:25]
	v_mfma_f32_16x16x32_bf16 v[22:25], v[176:179], v[200:203], v[22:25]
	v_mfma_f32_16x16x32_bf16 v[30:33], v[176:179], v[208:211], v[30:33]
	v_mfma_f32_16x16x32_bf16 v[30:33], v[180:183], v[212:215], v[30:33]
	v_mfma_f32_16x16x32_bf16 v[34:37], v[180:183], v[220:223], v[34:37]
	v_mfma_f32_16x16x32_bf16 v[34:37], v[176:179], v[216:219], v[34:37]
	v_mfma_f32_16x16x32_bf16 v[18:21], v[184:187], v[216:219], v[18:21]
	v_mfma_f32_16x16x32_bf16 v[18:21], v[188:191], v[220:223], v[18:21]
	v_mfma_f32_16x16x32_bf16 v[10:13], v[188:191], v[212:215], v[10:13]
	v_mfma_f32_16x16x32_bf16 v[10:13], v[184:187], v[208:211], v[10:13]
	v_mfma_f32_16x16x32_bf16 v[6:9], v[184:187], v[200:203], v[6:9]
	v_mfma_f32_16x16x32_bf16 v[6:9], v[188:191], v[204:207], v[6:9]
	v_mfma_f32_16x16x32_bf16 v[2:5], v[188:191], v[196:199], v[2:5]
	v_mfma_f32_16x16x32_bf16 v[2:5], v[184:187], v[192:195], v[2:5]
	s_barrier
	s_add_i32 s50, s70, s54
	s_mov_b32 m0, s50
	ds_read_b128 v[192:195], v163 offset:16384
	ds_read_b128 v[196:199], v163 offset:17408
	ds_read_b128 v[200:203], v163 offset:18432
	ds_read_b128 v[204:207], v163 offset:19456
	ds_read_b128 v[208:211], v163 offset:20480
	ds_read_b128 v[212:215], v163 offset:21504
	ds_read_b128 v[216:219], v163 offset:22528
	ds_read_b128 v[220:223], v163 offset:23552
	global_load_lds_dwordx4 v134, s[30:31]
	s_add_i32 m0, s50, 0x2000
	s_add_u32 s76, s30, 0x40000
	v_lshl_add_u64 v[226:227], s[30:31], 0, v[130:131]
	s_addc_u32 s77, s31, 0
	s_add_i32 s50, s71, s54
	global_load_lds_dwordx4 v130, s[30:31]
	s_mov_b32 m0, s50
	v_lshl_add_u64 v[230:231], s[34:35], 0, v[132:133]
	global_load_lds_dwordx4 v134, s[76:77]
	s_add_i32 m0, s50, 0x2000
	s_nop 0
	global_load_lds_dwordx4 v130, s[76:77]
	v_lshl_add_u64 v[228:229], s[34:35], 0, v[136:137]
	s_mov_b32 m0, s58
	s_nop 0
	global_load_lds_dwordx4 v136, s[34:35]
	s_mov_b32 m0, s59
	s_nop 0
	global_load_lds_dwordx4 v132, s[34:35]
	s_waitcnt vmcnt(8)
	s_waitcnt lgkmcnt(0)
	s_barrier
	v_mfma_f32_16x16x32_bf16 v[110:113], v[154:157], v[192:195], v[110:113]
	v_mfma_f32_16x16x32_bf16 v[110:113], v[164:167], v[196:199], v[110:113]
	v_mfma_f32_16x16x32_bf16 v[106:109], v[164:167], v[204:207], v[106:109]
	v_mfma_f32_16x16x32_bf16 v[106:109], v[154:157], v[200:203], v[106:109]
	v_mfma_f32_16x16x32_bf16 v[118:121], v[154:157], v[208:211], v[118:121]
	v_mfma_f32_16x16x32_bf16 v[118:121], v[164:167], v[212:215], v[118:121]
	v_mfma_f32_16x16x32_bf16 v[126:129], v[164:167], v[220:223], v[126:129]
	v_mfma_f32_16x16x32_bf16 v[126:129], v[154:157], v[216:219], v[126:129]
	v_mfma_f32_16x16x32_bf16 v[102:105], v[168:171], v[216:219], v[102:105]
	v_mfma_f32_16x16x32_bf16 v[102:105], v[172:175], v[220:223], v[102:105]
	v_mfma_f32_16x16x32_bf16 v[94:97], v[172:175], v[212:215], v[94:97]
	v_mfma_f32_16x16x32_bf16 v[94:97], v[168:171], v[208:211], v[94:97]
	v_mfma_f32_16x16x32_bf16 v[82:85], v[168:171], v[200:203], v[82:85]
	v_mfma_f32_16x16x32_bf16 v[82:85], v[172:175], v[204:207], v[82:85]
	v_mfma_f32_16x16x32_bf16 v[86:89], v[172:175], v[196:199], v[86:89]
	v_mfma_f32_16x16x32_bf16 v[86:89], v[168:171], v[192:195], v[86:89]
	v_mfma_f32_16x16x32_bf16 v[70:73], v[176:179], v[192:195], v[70:73]
	v_mfma_f32_16x16x32_bf16 v[70:73], v[180:183], v[196:199], v[70:73]
	v_mfma_f32_16x16x32_bf16 v[74:77], v[180:183], v[204:207], v[74:77]
	v_mfma_f32_16x16x32_bf16 v[74:77], v[176:179], v[200:203], v[74:77]
	v_mfma_f32_16x16x32_bf16 v[114:117], v[176:179], v[208:211], v[114:117]
	v_mfma_f32_16x16x32_bf16 v[114:117], v[180:183], v[212:215], v[114:117]
	v_mfma_f32_16x16x32_bf16 v[122:125], v[180:183], v[220:223], v[122:125]
	v_mfma_f32_16x16x32_bf16 v[122:125], v[176:179], v[216:219], v[122:125]
	v_mfma_f32_16x16x32_bf16 v[98:101], v[184:187], v[216:219], v[98:101]
	v_mfma_f32_16x16x32_bf16 v[98:101], v[188:191], v[220:223], v[98:101]
	v_mfma_f32_16x16x32_bf16 v[90:93], v[188:191], v[212:215], v[90:93]
	v_mfma_f32_16x16x32_bf16 v[90:93], v[184:187], v[208:211], v[90:93]
	v_mfma_f32_16x16x32_bf16 v[78:81], v[184:187], v[200:203], v[78:81]
	v_mfma_f32_16x16x32_bf16 v[78:81], v[188:191], v[204:207], v[78:81]
	v_mfma_f32_16x16x32_bf16 v[58:61], v[188:191], v[196:199], v[58:61]
	v_mfma_f32_16x16x32_bf16 v[58:61], v[184:187], v[192:195], v[58:61]
	s_barrier
	s_add_i32 s50, 0, 0x18000
	s_add_i32 s51, 0, 0x1c000
	v_add_u32_e32 v172, s50, v160
	v_add_u32_e32 v188, s51, v160
	ds_read_b128 v[154:157], v172
	ds_read_b128 v[164:167], v172 offset:1024
	ds_read_b128 v[168:171], v172 offset:2048
	ds_read_b128 v[172:175], v172 offset:3072
	ds_read_b128 v[176:179], v188
	ds_read_b128 v[180:183], v188 offset:1024
	ds_read_b128 v[184:187], v188 offset:2048
	ds_read_b128 v[188:191], v188 offset:3072
	s_add_u32 s34, s34, 0x40000
	s_addc_u32 s35, s35, 0
	s_mov_b32 m0, s60
	ds_read_b128 v[192:195], v163 offset:32768
	ds_read_b128 v[196:199], v163 offset:33792
	ds_read_b128 v[200:203], v163 offset:34816
	ds_read_b128 v[204:207], v163 offset:35840
	ds_read_b128 v[208:211], v163 offset:36864
	ds_read_b128 v[212:215], v163 offset:37888
	ds_read_b128 v[216:219], v163 offset:38912
	ds_read_b128 v[220:223], v163 offset:39936
	global_load_lds_dwordx4 v136, s[34:35]
	s_mov_b32 m0, s61
	s_nop 0
	global_load_lds_dwordx4 v132, s[34:35]
	s_waitcnt vmcnt(8)
	s_waitcnt lgkmcnt(0)
	s_barrier
	v_mfma_f32_16x16x32_bf16 v[42:45], v[154:157], v[192:195], v[42:45]
	v_mfma_f32_16x16x32_bf16 v[42:45], v[164:167], v[196:199], v[42:45]
	v_mfma_f32_16x16x32_bf16 v[54:57], v[164:167], v[204:207], v[54:57]
	v_mfma_f32_16x16x32_bf16 v[54:57], v[154:157], v[200:203], v[54:57]
	v_mfma_f32_16x16x32_bf16 v[66:69], v[154:157], v[208:211], v[66:69]
	v_mfma_f32_16x16x32_bf16 v[66:69], v[164:167], v[212:215], v[66:69]
	v_mfma_f32_16x16x32_bf16 v[62:65], v[164:167], v[220:223], v[62:65]
	v_mfma_f32_16x16x32_bf16 v[62:65], v[154:157], v[216:219], v[62:65]
	v_mfma_f32_16x16x32_bf16 v[46:49], v[168:171], v[216:219], v[46:49]
	v_mfma_f32_16x16x32_bf16 v[46:49], v[172:175], v[220:223], v[46:49]
	v_mfma_f32_16x16x32_bf16 v[50:53], v[172:175], v[212:215], v[50:53]
	v_mfma_f32_16x16x32_bf16 v[50:53], v[168:171], v[208:211], v[50:53]
	v_mfma_f32_16x16x32_bf16 v[38:41], v[168:171], v[200:203], v[38:41]
	v_mfma_f32_16x16x32_bf16 v[38:41], v[172:175], v[204:207], v[38:41]
	v_mfma_f32_16x16x32_bf16 v[26:29], v[172:175], v[196:199], v[26:29]
	v_mfma_f32_16x16x32_bf16 v[26:29], v[168:171], v[192:195], v[26:29]
	v_mfma_f32_16x16x32_bf16 v[14:17], v[176:179], v[192:195], v[14:17]
	v_mfma_f32_16x16x32_bf16 v[14:17], v[180:183], v[196:199], v[14:17]
	v_mfma_f32_16x16x32_bf16 v[22:25], v[180:183], v[204:207], v[22:25]
	v_mfma_f32_16x16x32_bf16 v[22:25], v[176:179], v[200:203], v[22:25]
	v_mfma_f32_16x16x32_bf16 v[30:33], v[176:179], v[208:211], v[30:33]
	v_mfma_f32_16x16x32_bf16 v[30:33], v[180:183], v[212:215], v[30:33]
	v_mfma_f32_16x16x32_bf16 v[34:37], v[180:183], v[220:223], v[34:37]
	v_mfma_f32_16x16x32_bf16 v[34:37], v[176:179], v[216:219], v[34:37]
	v_mfma_f32_16x16x32_bf16 v[18:21], v[184:187], v[216:219], v[18:21]
	v_mfma_f32_16x16x32_bf16 v[18:21], v[188:191], v[220:223], v[18:21]
	v_mfma_f32_16x16x32_bf16 v[10:13], v[188:191], v[212:215], v[10:13]
	v_mfma_f32_16x16x32_bf16 v[10:13], v[184:187], v[208:211], v[10:13]
	v_mfma_f32_16x16x32_bf16 v[6:9], v[184:187], v[200:203], v[6:9]
	v_mfma_f32_16x16x32_bf16 v[6:9], v[188:191], v[204:207], v[6:9]
	v_mfma_f32_16x16x32_bf16 v[2:5], v[188:191], v[196:199], v[2:5]
	v_mfma_f32_16x16x32_bf16 v[2:5], v[184:187], v[192:195], v[2:5]
	s_barrier
	s_add_i32 s34, s50, s54
	s_mov_b32 m0, s34
	ds_read_b128 v[192:195], v163 offset:49152
	ds_read_b128 v[196:199], v163 offset:50176
	ds_read_b128 v[200:203], v163 offset:51200
	ds_read_b128 v[204:207], v163 offset:52224
	ds_read_b128 v[208:211], v163 offset:53248
	ds_read_b128 v[212:215], v163 offset:54272
	ds_read_b128 v[216:219], v163 offset:55296
	ds_read_b128 v[220:223], v163 offset:56320
	s_add_u32 s98, s30, s10
	s_addc_u32 s99, s31, s11
	global_load_lds_dwordx4 v134, s[98:99]
	s_add_i32 m0, s34, 0x2000
	s_add_u32 s30, s30, 0x40080
	v_lshl_add_u64 v[224:225], v[226:227], 0, s[10:11]
	s_addc_u32 s31, s31, 0
	s_add_i32 s34, s51, s54
	global_load_lds_dwordx4 v[224:225], off
	s_mov_b32 m0, s34
	s_nop 0
	global_load_lds_dwordx4 v134, s[30:31]
	s_add_i32 m0, s34, 0x2000
	s_nop 0
	global_load_lds_dwordx4 v130, s[30:31]
	v_lshl_add_u64 v[224:225], v[228:229], 0, s[10:11]
	s_mov_b32 m0, s65
	s_nop 0
	global_load_lds_dwordx4 v[224:225], off
	v_lshl_add_u64 v[224:225], v[230:231], 0, s[10:11]
	s_mov_b32 m0, s66
	s_nop 0
	global_load_lds_dwordx4 v[224:225], off
	s_waitcnt vmcnt(8)
	s_waitcnt lgkmcnt(0)
	s_barrier
	v_mfma_f32_16x16x32_bf16 v[110:113], v[154:157], v[192:195], v[110:113]
	v_mfma_f32_16x16x32_bf16 v[110:113], v[164:167], v[196:199], v[110:113]
	v_mfma_f32_16x16x32_bf16 v[106:109], v[164:167], v[204:207], v[106:109]
	v_mfma_f32_16x16x32_bf16 v[106:109], v[154:157], v[200:203], v[106:109]
	v_mfma_f32_16x16x32_bf16 v[118:121], v[154:157], v[208:211], v[118:121]
	v_mfma_f32_16x16x32_bf16 v[118:121], v[164:167], v[212:215], v[118:121]
	v_mfma_f32_16x16x32_bf16 v[126:129], v[164:167], v[220:223], v[126:129]
	v_mfma_f32_16x16x32_bf16 v[126:129], v[154:157], v[216:219], v[126:129]
	v_mfma_f32_16x16x32_bf16 v[102:105], v[168:171], v[216:219], v[102:105]
	v_mfma_f32_16x16x32_bf16 v[102:105], v[172:175], v[220:223], v[102:105]
	v_mfma_f32_16x16x32_bf16 v[94:97], v[172:175], v[212:215], v[94:97]
	v_mfma_f32_16x16x32_bf16 v[94:97], v[168:171], v[208:211], v[94:97]
	v_mfma_f32_16x16x32_bf16 v[82:85], v[168:171], v[200:203], v[82:85]
	v_mfma_f32_16x16x32_bf16 v[82:85], v[172:175], v[204:207], v[82:85]
	v_mfma_f32_16x16x32_bf16 v[86:89], v[172:175], v[196:199], v[86:89]
	v_mfma_f32_16x16x32_bf16 v[86:89], v[168:171], v[192:195], v[86:89]
	v_mfma_f32_16x16x32_bf16 v[70:73], v[176:179], v[192:195], v[70:73]
	v_mfma_f32_16x16x32_bf16 v[70:73], v[180:183], v[196:199], v[70:73]
	v_mfma_f32_16x16x32_bf16 v[74:77], v[180:183], v[204:207], v[74:77]
	v_mfma_f32_16x16x32_bf16 v[74:77], v[176:179], v[200:203], v[74:77]
	v_mfma_f32_16x16x32_bf16 v[114:117], v[176:179], v[208:211], v[114:117]
	v_mfma_f32_16x16x32_bf16 v[114:117], v[180:183], v[212:215], v[114:117]
	v_mfma_f32_16x16x32_bf16 v[122:125], v[180:183], v[220:223], v[122:125]
	v_mfma_f32_16x16x32_bf16 v[122:125], v[176:179], v[216:219], v[122:125]
	v_mfma_f32_16x16x32_bf16 v[98:101], v[184:187], v[216:219], v[98:101]
	v_mfma_f32_16x16x32_bf16 v[98:101], v[188:191], v[220:223], v[98:101]
	v_mfma_f32_16x16x32_bf16 v[90:93], v[188:191], v[212:215], v[90:93]
	v_mfma_f32_16x16x32_bf16 v[90:93], v[184:187], v[208:211], v[90:93]
	v_mfma_f32_16x16x32_bf16 v[78:81], v[184:187], v[200:203], v[78:81]
	v_mfma_f32_16x16x32_bf16 v[78:81], v[188:191], v[204:207], v[78:81]
	v_mfma_f32_16x16x32_bf16 v[58:61], v[188:191], v[196:199], v[58:61]
	v_mfma_f32_16x16x32_bf16 v[58:61], v[184:187], v[192:195], v[58:61]
	s_barrier
	s_add_u32 s28, s28, 0x100
	s_addc_u32 s29, s29, 0
	s_add_u32 s17, s17, 0x100
	s_addc_u32 s19, s19, 0
	s_cmp_ge_i32 s75, s62
	s_mov_b32 s30, s75
	s_cbranch_scc0 .LBB0_256

.LBB0_351:
	v_add_u32_e32 v81, s62, v78
	s_waitcnt lgkmcnt(0)
	ds_read_b128 v[82:85], v81
	ds_read_b128 v[86:89], v81 offset:1024
	ds_read_b128 v[90:93], v81 offset:2048
	ds_read_b128 v[94:97], v81 offset:3072
	s_add_i32 s72, s24, 2
	s_add_u32 s22, s20, 0x100
	s_addc_u32 s23, s21, 0
	s_cmp_eq_u32 s61, s24
	s_cselect_b32 s24, s16, s70
	s_cselect_b32 s27, s15, s23
	s_cselect_b32 s26, s14, s22
	s_cselect_b32 s25, s17, s71
	s_mov_b32 m0, s63
	ds_read_b128 v[98:101], v79
	ds_read_b128 v[102:105], v79 offset:1024
	ds_read_b128 v[106:109], v79 offset:2048
	ds_read_b128 v[110:113], v79 offset:3072
	ds_read_b128 v[114:117], v79 offset:4096
	ds_read_b128 v[118:121], v79 offset:5120
	ds_read_b128 v[122:125], v79 offset:6144
	ds_read_b128 v[126:129], v79 offset:7168
	global_load_lds_dwordx4 v74, s[20:21]
	s_mov_b32 m0, s64
	s_nop 0
	global_load_lds_dwordx4 v76, s[20:21]
	s_waitcnt vmcnt(8)
	s_waitcnt lgkmcnt(0)
	s_barrier
	v_mfma_f32_16x16x32_bf16 v[62:65], v[82:85], v[98:101], v[62:65]
	v_mfma_f32_16x16x32_bf16 v[62:65], v[86:89], v[102:105], v[62:65]
	v_mfma_f32_16x16x32_bf16 v[54:57], v[86:89], v[110:113], v[54:57]
	v_mfma_f32_16x16x32_bf16 v[54:57], v[82:85], v[106:109], v[54:57]
	v_mfma_f32_16x16x32_bf16 v[46:49], v[82:85], v[114:117], v[46:49]
	v_mfma_f32_16x16x32_bf16 v[46:49], v[86:89], v[118:121], v[46:49]
	v_mfma_f32_16x16x32_bf16 v[34:37], v[86:89], v[126:129], v[34:37]
	v_mfma_f32_16x16x32_bf16 v[34:37], v[82:85], v[122:125], v[34:37]
	v_mfma_f32_16x16x32_bf16 v[26:29], v[90:93], v[122:125], v[26:29]
	v_mfma_f32_16x16x32_bf16 v[26:29], v[94:97], v[126:129], v[26:29]
	v_mfma_f32_16x16x32_bf16 v[42:45], v[94:97], v[118:121], v[42:45]
	v_mfma_f32_16x16x32_bf16 v[42:45], v[90:93], v[114:117], v[42:45]
	v_mfma_f32_16x16x32_bf16 v[50:53], v[90:93], v[106:109], v[50:53]
	v_mfma_f32_16x16x32_bf16 v[50:53], v[94:97], v[110:113], v[50:53]
	v_mfma_f32_16x16x32_bf16 v[58:61], v[94:97], v[102:105], v[58:61]
	v_mfma_f32_16x16x32_bf16 v[58:61], v[90:93], v[98:101], v[58:61]
	s_barrier
	s_mov_b32 m0, s65
	s_add_u32 s20, s24, 0x10000
	ds_read_b128 v[98:101], v79 offset:16384
	ds_read_b128 v[102:105], v79 offset:17408
	ds_read_b128 v[106:109], v79 offset:18432
	ds_read_b128 v[110:113], v79 offset:19456
	ds_read_b128 v[114:117], v79 offset:20480
	ds_read_b128 v[118:121], v79 offset:21504
	ds_read_b128 v[122:125], v79 offset:22528
	ds_read_b128 v[126:129], v79 offset:23552
	global_load_lds_dwordx4 v70, s[24:25]
	s_mov_b32 m0, s66
	s_addc_u32 s21, s25, 0
	global_load_lds_dwordx4 v66, s[24:25]
	s_mov_b32 m0, s34
	global_load_lds_dwordx4 v70, s[20:21]
	s_mov_b32 m0, s35
	s_nop 0
	global_load_lds_dwordx4 v66, s[20:21]
	s_mov_b32 m0, s31
	s_nop 0
	global_load_lds_dwordx4 v72, s[26:27]
	s_mov_b32 m0, s52
	s_nop 0
	global_load_lds_dwordx4 v68, s[26:27]
	s_waitcnt vmcnt(8)
	s_waitcnt lgkmcnt(0)
	s_barrier
	v_mfma_f32_16x16x32_bf16 v[38:41], v[82:85], v[98:101], v[38:41]
	v_mfma_f32_16x16x32_bf16 v[38:41], v[86:89], v[102:105], v[38:41]
	v_mfma_f32_16x16x32_bf16 v[22:25], v[86:89], v[110:113], v[22:25]
	v_mfma_f32_16x16x32_bf16 v[22:25], v[82:85], v[106:109], v[22:25]
	v_mfma_f32_16x16x32_bf16 v[14:17], v[82:85], v[114:117], v[14:17]
	v_mfma_f32_16x16x32_bf16 v[14:17], v[86:89], v[118:121], v[14:17]
	v_mfma_f32_16x16x32_bf16 v[6:9], v[86:89], v[126:129], v[6:9]
	v_mfma_f32_16x16x32_bf16 v[6:9], v[82:85], v[122:125], v[6:9]
	v_mfma_f32_16x16x32_bf16 v[2:5], v[90:93], v[122:125], v[2:5]
	v_mfma_f32_16x16x32_bf16 v[2:5], v[94:97], v[126:129], v[2:5]
	v_mfma_f32_16x16x32_bf16 v[10:13], v[94:97], v[118:121], v[10:13]
	v_mfma_f32_16x16x32_bf16 v[10:13], v[90:93], v[114:117], v[10:13]
	v_mfma_f32_16x16x32_bf16 v[18:21], v[90:93], v[106:109], v[18:21]
	v_mfma_f32_16x16x32_bf16 v[18:21], v[94:97], v[110:113], v[18:21]
	v_mfma_f32_16x16x32_bf16 v[30:33], v[94:97], v[102:105], v[30:33]
	v_mfma_f32_16x16x32_bf16 v[30:33], v[90:93], v[98:101], v[30:33]
	s_barrier
	v_add_u32_e32 v81, s67, v78
	ds_read_b128 v[82:85], v81
	ds_read_b128 v[86:89], v81 offset:1024
	ds_read_b128 v[90:93], v81 offset:2048
	ds_read_b128 v[94:97], v81 offset:3072
	s_add_u32 s20, s26, 0x18000
	s_addc_u32 s21, s27, 0
	s_mov_b32 m0, s53
	ds_read_b128 v[98:101], v79 offset:32768
	ds_read_b128 v[102:105], v79 offset:33792
	ds_read_b128 v[106:109], v79 offset:34816
	ds_read_b128 v[110:113], v79 offset:35840
	ds_read_b128 v[114:117], v79 offset:36864
	ds_read_b128 v[118:121], v79 offset:37888
	ds_read_b128 v[122:125], v79 offset:38912
	ds_read_b128 v[126:129], v79 offset:39936
	global_load_lds_dwordx4 v72, s[20:21]
	s_mov_b32 m0, s54
	s_nop 0
	global_load_lds_dwordx4 v68, s[20:21]
	s_waitcnt vmcnt(8)
	s_waitcnt lgkmcnt(0)
	s_barrier
	v_mfma_f32_16x16x32_bf16 v[62:65], v[82:85], v[98:101], v[62:65]
	v_mfma_f32_16x16x32_bf16 v[62:65], v[86:89], v[102:105], v[62:65]
	v_mfma_f32_16x16x32_bf16 v[54:57], v[86:89], v[110:113], v[54:57]
	v_mfma_f32_16x16x32_bf16 v[54:57], v[82:85], v[106:109], v[54:57]
	v_mfma_f32_16x16x32_bf16 v[46:49], v[82:85], v[114:117], v[46:49]
	v_mfma_f32_16x16x32_bf16 v[46:49], v[86:89], v[118:121], v[46:49]
	v_mfma_f32_16x16x32_bf16 v[34:37], v[86:89], v[126:129], v[34:37]
	v_mfma_f32_16x16x32_bf16 v[34:37], v[82:85], v[122:125], v[34:37]
	v_mfma_f32_16x16x32_bf16 v[26:29], v[90:93], v[122:125], v[26:29]
	v_mfma_f32_16x16x32_bf16 v[26:29], v[94:97], v[126:129], v[26:29]
	v_mfma_f32_16x16x32_bf16 v[42:45], v[94:97], v[118:121], v[42:45]
	v_mfma_f32_16x16x32_bf16 v[42:45], v[90:93], v[114:117], v[42:45]
	v_mfma_f32_16x16x32_bf16 v[50:53], v[90:93], v[106:109], v[50:53]
	v_mfma_f32_16x16x32_bf16 v[50:53], v[94:97], v[110:113], v[50:53]
	v_mfma_f32_16x16x32_bf16 v[58:61], v[94:97], v[102:105], v[58:61]
	v_mfma_f32_16x16x32_bf16 v[58:61], v[90:93], v[98:101], v[58:61]
	s_barrier
	s_mov_b32 m0, s68
	s_add_u32 s20, s24, 0x10080
	ds_read_b128 v[98:101], v79 offset:49152
	ds_read_b128 v[102:105], v79 offset:50176
	ds_read_b128 v[106:109], v79 offset:51200
	ds_read_b128 v[110:113], v79 offset:52224
	ds_read_b128 v[114:117], v79 offset:53248
	ds_read_b128 v[118:121], v79 offset:54272
	ds_read_b128 v[122:125], v79 offset:55296
	ds_read_b128 v[126:129], v79 offset:56320
	s_add_u32 s98, s24, s6
	s_addc_u32 s99, s25, s7
	global_load_lds_dwordx4 v70, s[98:99]
	s_mov_b32 m0, s69
	s_addc_u32 s21, s25, 0
	s_add_u32 s100, s24, s6
	s_addc_u32 s101, s25, s7
	global_load_lds_dwordx4 v66, s[100:101]
	s_mov_b32 m0, s59
	s_nop 0
	global_load_lds_dwordx4 v70, s[20:21]
	s_mov_b32 m0, s60
	s_nop 0
	global_load_lds_dwordx4 v66, s[20:21]
	s_mov_b32 m0, s57
	s_nop 0
	s_add_u32 s98, s26, s6
	s_addc_u32 s99, s27, s7
	global_load_lds_dwordx4 v72, s[98:99]
	s_mov_b32 m0, s58
	s_nop 0
	s_add_u32 s100, s26, s6
	s_addc_u32 s101, s27, s7
	global_load_lds_dwordx4 v68, s[100:101]
	s_waitcnt vmcnt(8)
	s_waitcnt lgkmcnt(0)
	s_barrier
	v_mfma_f32_16x16x32_bf16 v[38:41], v[82:85], v[98:101], v[38:41]
	v_mfma_f32_16x16x32_bf16 v[38:41], v[86:89], v[102:105], v[38:41]
	v_mfma_f32_16x16x32_bf16 v[22:25], v[86:89], v[110:113], v[22:25]
	v_mfma_f32_16x16x32_bf16 v[22:25], v[82:85], v[106:109], v[22:25]
	v_mfma_f32_16x16x32_bf16 v[14:17], v[82:85], v[114:117], v[14:17]
	v_mfma_f32_16x16x32_bf16 v[14:17], v[86:89], v[118:121], v[14:17]
	v_mfma_f32_16x16x32_bf16 v[6:9], v[86:89], v[126:129], v[6:9]
	v_mfma_f32_16x16x32_bf16 v[6:9], v[82:85], v[122:125], v[6:9]
	v_mfma_f32_16x16x32_bf16 v[2:5], v[90:93], v[122:125], v[2:5]
	v_mfma_f32_16x16x32_bf16 v[2:5], v[94:97], v[126:129], v[2:5]
	v_mfma_f32_16x16x32_bf16 v[10:13], v[94:97], v[118:121], v[10:13]
	v_mfma_f32_16x16x32_bf16 v[10:13], v[90:93], v[114:117], v[10:13]
	v_mfma_f32_16x16x32_bf16 v[18:21], v[90:93], v[106:109], v[18:21]
	v_mfma_f32_16x16x32_bf16 v[18:21], v[94:97], v[110:113], v[18:21]
	v_mfma_f32_16x16x32_bf16 v[30:33], v[94:97], v[102:105], v[30:33]
	v_mfma_f32_16x16x32_bf16 v[30:33], v[90:93], v[98:101], v[30:33]
	s_barrier
	s_add_u32 s70, s70, 0x100
	s_addc_u32 s71, s71, 0
	s_cmp_ge_i32 s72, s56
	s_mov_b64 s[20:21], s[22:23]
	s_mov_b32 s24, s72
	s_cbranch_scc0 .LBB0_351

.LBB0_468:
	v_add_u32_e32 v144, s62, v1
	ds_read_b128 v[150:153], v144
	ds_read_b128 v[154:157], v144 offset:1024
	ds_read_b128 v[158:161], v144 offset:2048
	ds_read_b128 v[162:165], v144 offset:3072
	v_add_u32_e32 v144, s63, v1
	ds_read_b128 v[166:169], v144
	ds_read_b128 v[170:173], v144 offset:1024
	ds_read_b128 v[174:177], v144 offset:2048
	ds_read_b128 v[178:181], v144 offset:3072
	s_add_i32 s77, s26, 2
	s_add_u32 s24, s22, 0x100
	s_addc_u32 s25, s23, 0
	s_cmp_eq_u32 s61, s26
	s_cselect_b32 s26, s16, s75
	s_cselect_b32 s29, s15, s25
	s_cselect_b32 s28, s14, s24
	s_cselect_b32 s27, s17, s76
	s_mov_b32 m0, s64
	ds_read_b128 v[182:185], v149
	ds_read_b128 v[186:189], v149 offset:1024
	ds_read_b128 v[190:193], v149 offset:2048
	ds_read_b128 v[194:197], v149 offset:3072
	ds_read_b128 v[198:201], v149 offset:4096
	ds_read_b128 v[202:205], v149 offset:5120
	ds_read_b128 v[206:209], v149 offset:6144
	ds_read_b128 v[210:213], v149 offset:7168
	global_load_lds_dwordx4 v140, s[22:23]
	s_mov_b32 m0, s65
	s_nop 0
	global_load_lds_dwordx4 v142, s[22:23]
	s_waitcnt vmcnt(8)
	s_waitcnt lgkmcnt(0)
	s_barrier
	v_mfma_f32_16x16x32_bf16 v[126:129], v[150:153], v[182:185], v[126:129]
	v_mfma_f32_16x16x32_bf16 v[126:129], v[154:157], v[186:189], v[126:129]
	v_mfma_f32_16x16x32_bf16 v[110:113], v[154:157], v[194:197], v[110:113]
	v_mfma_f32_16x16x32_bf16 v[110:113], v[150:153], v[190:193], v[110:113]
	v_mfma_f32_16x16x32_bf16 v[94:97], v[150:153], v[198:201], v[94:97]
	v_mfma_f32_16x16x32_bf16 v[94:97], v[154:157], v[202:205], v[94:97]
	v_mfma_f32_16x16x32_bf16 v[78:81], v[154:157], v[210:213], v[78:81]
	v_mfma_f32_16x16x32_bf16 v[78:81], v[150:153], v[206:209], v[78:81]
	v_mfma_f32_16x16x32_bf16 v[74:77], v[158:161], v[206:209], v[74:77]
	v_mfma_f32_16x16x32_bf16 v[74:77], v[162:165], v[210:213], v[74:77]
	v_mfma_f32_16x16x32_bf16 v[90:93], v[162:165], v[202:205], v[90:93]
	v_mfma_f32_16x16x32_bf16 v[90:93], v[158:161], v[198:201], v[90:93]
	v_mfma_f32_16x16x32_bf16 v[106:109], v[158:161], v[190:193], v[106:109]
	v_mfma_f32_16x16x32_bf16 v[106:109], v[162:165], v[194:197], v[106:109]
	v_mfma_f32_16x16x32_bf16 v[122:125], v[162:165], v[186:189], v[122:125]
	v_mfma_f32_16x16x32_bf16 v[122:125], v[158:161], v[182:185], v[122:125]
	v_mfma_f32_16x16x32_bf16 v[118:121], v[166:169], v[182:185], v[118:121]
	v_mfma_f32_16x16x32_bf16 v[118:121], v[170:173], v[186:189], v[118:121]
	v_mfma_f32_16x16x32_bf16 v[102:105], v[170:173], v[194:197], v[102:105]
	v_mfma_f32_16x16x32_bf16 v[102:105], v[166:169], v[190:193], v[102:105]
	v_mfma_f32_16x16x32_bf16 v[86:89], v[166:169], v[198:201], v[86:89]
	v_mfma_f32_16x16x32_bf16 v[86:89], v[170:173], v[202:205], v[86:89]
	v_mfma_f32_16x16x32_bf16 v[70:73], v[170:173], v[210:213], v[70:73]
	v_mfma_f32_16x16x32_bf16 v[70:73], v[166:169], v[206:209], v[70:73]
	v_mfma_f32_16x16x32_bf16 v[66:69], v[174:177], v[206:209], v[66:69]
	v_mfma_f32_16x16x32_bf16 v[66:69], v[178:181], v[210:213], v[66:69]
	v_mfma_f32_16x16x32_bf16 v[82:85], v[178:181], v[202:205], v[82:85]
	v_mfma_f32_16x16x32_bf16 v[82:85], v[174:177], v[198:201], v[82:85]
	v_mfma_f32_16x16x32_bf16 v[98:101], v[174:177], v[190:193], v[98:101]
	v_mfma_f32_16x16x32_bf16 v[98:101], v[178:181], v[194:197], v[98:101]
	v_mfma_f32_16x16x32_bf16 v[114:117], v[178:181], v[186:189], v[114:117]
	v_mfma_f32_16x16x32_bf16 v[114:117], v[174:177], v[182:185], v[114:117]
	s_barrier
	s_mov_b32 m0, s66
	s_add_u32 s22, s26, 0x18000
	ds_read_b128 v[182:185], v149 offset:16384
	ds_read_b128 v[186:189], v149 offset:17408
	ds_read_b128 v[190:193], v149 offset:18432
	ds_read_b128 v[194:197], v149 offset:19456
	ds_read_b128 v[198:201], v149 offset:20480
	ds_read_b128 v[202:205], v149 offset:21504
	ds_read_b128 v[206:209], v149 offset:22528
	ds_read_b128 v[210:213], v149 offset:23552
	global_load_lds_dwordx4 v134, s[26:27]
	v_lshl_add_u64 v[214:215], s[26:27], 0, v[130:131]
	s_mov_b32 m0, s67
	s_addc_u32 s23, s27, 0
	global_load_lds_dwordx4 v130, s[26:27]
	s_mov_b32 m0, s68
	global_load_lds_dwordx4 v134, s[22:23]
	s_mov_b32 m0, s69
	s_nop 0
	global_load_lds_dwordx4 v130, s[22:23]
	s_mov_b32 m0, s34
	s_nop 0
	global_load_lds_dwordx4 v136, s[28:29]
	s_mov_b32 m0, s35
	s_nop 0
	global_load_lds_dwordx4 v132, s[28:29]
	s_waitcnt vmcnt(8)
	s_waitcnt lgkmcnt(0)
	s_barrier
	v_mfma_f32_16x16x32_bf16 v[62:65], v[150:153], v[182:185], v[62:65]
	v_mfma_f32_16x16x32_bf16 v[62:65], v[154:157], v[186:189], v[62:65]
	v_mfma_f32_16x16x32_bf16 v[46:49], v[154:157], v[194:197], v[46:49]
	v_mfma_f32_16x16x32_bf16 v[46:49], v[150:153], v[190:193], v[46:49]
	v_mfma_f32_16x16x32_bf16 v[30:33], v[150:153], v[198:201], v[30:33]
	v_mfma_f32_16x16x32_bf16 v[30:33], v[154:157], v[202:205], v[30:33]
	v_mfma_f32_16x16x32_bf16 v[14:17], v[154:157], v[210:213], v[14:17]
	v_mfma_f32_16x16x32_bf16 v[14:17], v[150:153], v[206:209], v[14:17]
	v_mfma_f32_16x16x32_bf16 v[10:13], v[158:161], v[206:209], v[10:13]
	v_mfma_f32_16x16x32_bf16 v[10:13], v[162:165], v[210:213], v[10:13]
	v_mfma_f32_16x16x32_bf16 v[26:29], v[162:165], v[202:205], v[26:29]
	v_mfma_f32_16x16x32_bf16 v[26:29], v[158:161], v[198:201], v[26:29]
	v_mfma_f32_16x16x32_bf16 v[42:45], v[158:161], v[190:193], v[42:45]
	v_mfma_f32_16x16x32_bf16 v[42:45], v[162:165], v[194:197], v[42:45]
	v_mfma_f32_16x16x32_bf16 v[58:61], v[162:165], v[186:189], v[58:61]
	v_mfma_f32_16x16x32_bf16 v[58:61], v[158:161], v[182:185], v[58:61]
	v_mfma_f32_16x16x32_bf16 v[54:57], v[166:169], v[182:185], v[54:57]
	v_mfma_f32_16x16x32_bf16 v[54:57], v[170:173], v[186:189], v[54:57]
	v_mfma_f32_16x16x32_bf16 v[38:41], v[170:173], v[194:197], v[38:41]
	v_mfma_f32_16x16x32_bf16 v[38:41], v[166:169], v[190:193], v[38:41]
	v_mfma_f32_16x16x32_bf16 v[22:25], v[166:169], v[198:201], v[22:25]
	v_mfma_f32_16x16x32_bf16 v[22:25], v[170:173], v[202:205], v[22:25]
	v_mfma_f32_16x16x32_bf16 v[6:9], v[170:173], v[210:213], v[6:9]
	v_mfma_f32_16x16x32_bf16 v[6:9], v[166:169], v[206:209], v[6:9]
	v_mfma_f32_16x16x32_bf16 v[2:5], v[174:177], v[206:209], v[2:5]
	v_mfma_f32_16x16x32_bf16 v[2:5], v[178:181], v[210:213], v[2:5]
	v_mfma_f32_16x16x32_bf16 v[18:21], v[178:181], v[202:205], v[18:21]
	v_mfma_f32_16x16x32_bf16 v[18:21], v[174:177], v[198:201], v[18:21]
	v_mfma_f32_16x16x32_bf16 v[34:37], v[174:177], v[190:193], v[34:37]
	v_mfma_f32_16x16x32_bf16 v[34:37], v[178:181], v[194:197], v[34:37]
	v_mfma_f32_16x16x32_bf16 v[50:53], v[178:181], v[186:189], v[50:53]
	v_mfma_f32_16x16x32_bf16 v[50:53], v[174:177], v[182:185], v[50:53]
	s_barrier
	v_add_u32_e32 v162, s70, v1
	v_add_u32_e32 v178, s71, v1
	ds_read_b128 v[150:153], v162
	ds_read_b128 v[154:157], v162 offset:1024
	ds_read_b128 v[158:161], v162 offset:2048
	ds_read_b128 v[162:165], v162 offset:3072
	ds_read_b128 v[166:169], v178
	ds_read_b128 v[170:173], v178 offset:1024
	ds_read_b128 v[174:177], v178 offset:2048
	ds_read_b128 v[178:181], v178 offset:3072
	s_add_u32 s22, s28, 0x18000
	s_addc_u32 s23, s29, 0
	s_mov_b32 m0, s52
	ds_read_b128 v[182:185], v149 offset:32768
	ds_read_b128 v[186:189], v149 offset:33792
	ds_read_b128 v[190:193], v149 offset:34816
	ds_read_b128 v[194:197], v149 offset:35840
	ds_read_b128 v[198:201], v149 offset:36864
	ds_read_b128 v[202:205], v149 offset:37888
	ds_read_b128 v[206:209], v149 offset:38912
	ds_read_b128 v[210:213], v149 offset:39936
	global_load_lds_dwordx4 v136, s[22:23]
	s_mov_b32 m0, s53
	s_nop 0
	global_load_lds_dwordx4 v132, s[22:23]
	s_waitcnt vmcnt(8)
	s_waitcnt lgkmcnt(0)
	s_barrier
	v_mfma_f32_16x16x32_bf16 v[126:129], v[150:153], v[182:185], v[126:129]
	v_mfma_f32_16x16x32_bf16 v[126:129], v[154:157], v[186:189], v[126:129]
	v_mfma_f32_16x16x32_bf16 v[110:113], v[154:157], v[194:197], v[110:113]
	v_mfma_f32_16x16x32_bf16 v[110:113], v[150:153], v[190:193], v[110:113]
	v_mfma_f32_16x16x32_bf16 v[94:97], v[150:153], v[198:201], v[94:97]
	v_mfma_f32_16x16x32_bf16 v[94:97], v[154:157], v[202:205], v[94:97]
	v_mfma_f32_16x16x32_bf16 v[78:81], v[154:157], v[210:213], v[78:81]
	v_mfma_f32_16x16x32_bf16 v[78:81], v[150:153], v[206:209], v[78:81]
	v_mfma_f32_16x16x32_bf16 v[74:77], v[158:161], v[206:209], v[74:77]
	v_mfma_f32_16x16x32_bf16 v[74:77], v[162:165], v[210:213], v[74:77]
	v_mfma_f32_16x16x32_bf16 v[90:93], v[162:165], v[202:205], v[90:93]
	v_mfma_f32_16x16x32_bf16 v[90:93], v[158:161], v[198:201], v[90:93]
	v_mfma_f32_16x16x32_bf16 v[106:109], v[158:161], v[190:193], v[106:109]
	v_mfma_f32_16x16x32_bf16 v[106:109], v[162:165], v[194:197], v[106:109]
	v_mfma_f32_16x16x32_bf16 v[122:125], v[162:165], v[186:189], v[122:125]
	v_mfma_f32_16x16x32_bf16 v[122:125], v[158:161], v[182:185], v[122:125]
	v_mfma_f32_16x16x32_bf16 v[118:121], v[166:169], v[182:185], v[118:121]
	v_mfma_f32_16x16x32_bf16 v[118:121], v[170:173], v[186:189], v[118:121]
	v_mfma_f32_16x16x32_bf16 v[102:105], v[170:173], v[194:197], v[102:105]
	v_mfma_f32_16x16x32_bf16 v[102:105], v[166:169], v[190:193], v[102:105]
	v_mfma_f32_16x16x32_bf16 v[86:89], v[166:169], v[198:201], v[86:89]
	v_mfma_f32_16x16x32_bf16 v[86:89], v[170:173], v[202:205], v[86:89]
	v_mfma_f32_16x16x32_bf16 v[70:73], v[170:173], v[210:213], v[70:73]
	v_mfma_f32_16x16x32_bf16 v[70:73], v[166:169], v[206:209], v[70:73]
	v_mfma_f32_16x16x32_bf16 v[66:69], v[174:177], v[206:209], v[66:69]
	v_mfma_f32_16x16x32_bf16 v[66:69], v[178:181], v[210:213], v[66:69]
	v_mfma_f32_16x16x32_bf16 v[82:85], v[178:181], v[202:205], v[82:85]
	v_mfma_f32_16x16x32_bf16 v[82:85], v[174:177], v[198:201], v[82:85]
	v_mfma_f32_16x16x32_bf16 v[98:101], v[174:177], v[190:193], v[98:101]
	v_mfma_f32_16x16x32_bf16 v[98:101], v[178:181], v[194:197], v[98:101]
	v_mfma_f32_16x16x32_bf16 v[114:117], v[178:181], v[186:189], v[114:117]
	v_mfma_f32_16x16x32_bf16 v[114:117], v[174:177], v[182:185], v[114:117]
	s_barrier
	s_mov_b32 m0, s72
	ds_read_b128 v[182:185], v149 offset:49152
	ds_read_b128 v[186:189], v149 offset:50176
	ds_read_b128 v[190:193], v149 offset:51200
	ds_read_b128 v[194:197], v149 offset:52224
	ds_read_b128 v[198:201], v149 offset:53248
	ds_read_b128 v[202:205], v149 offset:54272
	ds_read_b128 v[206:209], v149 offset:55296
	ds_read_b128 v[210:213], v149 offset:56320
	s_add_u32 s98, s26, s4
	s_addc_u32 s99, s27, s5
	global_load_lds_dwordx4 v134, s[98:99]
	s_add_i32 m0, s72, 0x2000
	s_add_u32 s22, s26, 0x18080
	v_lshl_add_u64 v[144:145], v[214:215], 0, s[4:5]
	s_addc_u32 s23, s27, 0
	s_add_i32 s26, s71, s30
	global_load_lds_dwordx4 v[144:145], off
	s_mov_b32 m0, s26
	s_nop 0
	global_load_lds_dwordx4 v134, s[22:23]
	s_add_i32 m0, s26, 0x2000
	s_nop 0
	global_load_lds_dwordx4 v130, s[22:23]
	s_mov_b32 m0, s59
	s_nop 0
	s_add_u32 s100, s28, s4
	s_addc_u32 s101, s29, s5
	global_load_lds_dwordx4 v136, s[100:101]
	s_mov_b32 m0, s60
	s_nop 0
	s_add_u32 s98, s28, s4
	s_addc_u32 s99, s29, s5
	global_load_lds_dwordx4 v132, s[98:99]
	s_waitcnt vmcnt(8)
	s_waitcnt lgkmcnt(0)
	s_barrier
	v_mfma_f32_16x16x32_bf16 v[62:65], v[150:153], v[182:185], v[62:65]
	v_mfma_f32_16x16x32_bf16 v[62:65], v[154:157], v[186:189], v[62:65]
	v_mfma_f32_16x16x32_bf16 v[46:49], v[154:157], v[194:197], v[46:49]
	v_mfma_f32_16x16x32_bf16 v[46:49], v[150:153], v[190:193], v[46:49]
	v_mfma_f32_16x16x32_bf16 v[30:33], v[150:153], v[198:201], v[30:33]
	v_mfma_f32_16x16x32_bf16 v[30:33], v[154:157], v[202:205], v[30:33]
	v_mfma_f32_16x16x32_bf16 v[14:17], v[154:157], v[210:213], v[14:17]
	v_mfma_f32_16x16x32_bf16 v[14:17], v[150:153], v[206:209], v[14:17]
	v_mfma_f32_16x16x32_bf16 v[10:13], v[158:161], v[206:209], v[10:13]
	v_mfma_f32_16x16x32_bf16 v[10:13], v[162:165], v[210:213], v[10:13]
	v_mfma_f32_16x16x32_bf16 v[26:29], v[162:165], v[202:205], v[26:29]
	v_mfma_f32_16x16x32_bf16 v[26:29], v[158:161], v[198:201], v[26:29]
	v_mfma_f32_16x16x32_bf16 v[42:45], v[158:161], v[190:193], v[42:45]
	v_mfma_f32_16x16x32_bf16 v[42:45], v[162:165], v[194:197], v[42:45]
	v_mfma_f32_16x16x32_bf16 v[58:61], v[162:165], v[186:189], v[58:61]
	v_mfma_f32_16x16x32_bf16 v[58:61], v[158:161], v[182:185], v[58:61]
	v_mfma_f32_16x16x32_bf16 v[54:57], v[166:169], v[182:185], v[54:57]
	v_mfma_f32_16x16x32_bf16 v[54:57], v[170:173], v[186:189], v[54:57]
	v_mfma_f32_16x16x32_bf16 v[38:41], v[170:173], v[194:197], v[38:41]
	v_mfma_f32_16x16x32_bf16 v[38:41], v[166:169], v[190:193], v[38:41]
	v_mfma_f32_16x16x32_bf16 v[22:25], v[166:169], v[198:201], v[22:25]
	v_mfma_f32_16x16x32_bf16 v[22:25], v[170:173], v[202:205], v[22:25]
	v_mfma_f32_16x16x32_bf16 v[6:9], v[170:173], v[210:213], v[6:9]
	v_mfma_f32_16x16x32_bf16 v[6:9], v[166:169], v[206:209], v[6:9]
	v_mfma_f32_16x16x32_bf16 v[2:5], v[174:177], v[206:209], v[2:5]
	v_mfma_f32_16x16x32_bf16 v[2:5], v[178:181], v[210:213], v[2:5]
	v_mfma_f32_16x16x32_bf16 v[18:21], v[178:181], v[202:205], v[18:21]
	v_mfma_f32_16x16x32_bf16 v[18:21], v[174:177], v[198:201], v[18:21]
	v_mfma_f32_16x16x32_bf16 v[34:37], v[174:177], v[190:193], v[34:37]
	v_mfma_f32_16x16x32_bf16 v[34:37], v[178:181], v[194:197], v[34:37]
	v_mfma_f32_16x16x32_bf16 v[50:53], v[178:181], v[186:189], v[50:53]
	v_mfma_f32_16x16x32_bf16 v[50:53], v[174:177], v[182:185], v[50:53]
	s_barrier
	s_add_u32 s75, s75, 0x100
	s_addc_u32 s76, s76, 0
	s_cmp_ge_i32 s77, s57
	s_mov_b64 s[22:23], s[24:25]
	s_mov_b32 s26, s77
	s_cbranch_scc0 .LBB0_468

.LBB0_599:
	v_add_u32_e32 v142, s74, v199
	v_add_u32_e32 v162, s75, v199
	ds_read_b128 v[130:133], v142
	ds_read_b128 v[134:137], v142 offset:1024
	ds_read_b128 v[138:141], v142 offset:2048
	ds_read_b128 v[142:145], v142 offset:3072
	ds_read_b128 v[146:149], v162
	ds_read_b128 v[150:153], v162 offset:1024
	ds_read_b128 v[174:177], v162 offset:2048
	ds_read_b128 v[178:181], v162 offset:3072
	s_add_i32 s31, s52, 2
	s_add_u32 s50, s34, 0x3ff000
	s_addc_u32 s51, s35, 0
	s_cmp_eq_u32 s71, s52
	s_cselect_b32 s56, s26, s50
	s_cselect_b32 s57, s27, s51
	s_cselect_b32 s54, s28, s23
	s_cselect_b32 s55, s29, s25
	s_add_u32 s52, s56, 0x400000
	s_addc_u32 s53, s57, 0
	s_add_i32 m0, s59, 0xc000
	ds_read_b128 v[182:185], v200
	ds_read_b128 v[186:189], v200 offset:1024
	ds_read_b128 v[190:193], v200 offset:2048
	ds_read_b128 v[194:197], v200 offset:3072
	ds_read_b128 v[202:205], v200 offset:4096
	ds_read_b128 v[206:209], v200 offset:5120
	ds_read_b128 v[210:213], v200 offset:6144
	ds_read_b128 v[214:217], v200 offset:7168
	global_load_lds_dwordx4 v164, s[34:35]
	s_add_i32 m0, s59, 0xe000
	s_nop 0
	global_load_lds_dwordx4 v166, s[34:35]
	s_waitcnt vmcnt(8)
	s_waitcnt lgkmcnt(0)
	s_barrier
	v_mfma_f32_16x16x32_bf16 v[118:121], v[130:133], v[182:185], v[118:121]
	v_mfma_f32_16x16x32_bf16 v[118:121], v[134:137], v[186:189], v[118:121]
	v_mfma_f32_16x16x32_bf16 v[110:113], v[134:137], v[194:197], v[110:113]
	v_mfma_f32_16x16x32_bf16 v[110:113], v[130:133], v[190:193], v[110:113]
	v_mfma_f32_16x16x32_bf16 v[94:97], v[130:133], v[202:205], v[94:97]
	v_mfma_f32_16x16x32_bf16 v[94:97], v[134:137], v[206:209], v[94:97]
	v_mfma_f32_16x16x32_bf16 v[78:81], v[134:137], v[214:217], v[78:81]
	v_mfma_f32_16x16x32_bf16 v[78:81], v[130:133], v[210:213], v[78:81]
	v_mfma_f32_16x16x32_bf16 v[74:77], v[138:141], v[210:213], v[74:77]
	v_mfma_f32_16x16x32_bf16 v[74:77], v[142:145], v[214:217], v[74:77]
	v_mfma_f32_16x16x32_bf16 v[90:93], v[142:145], v[206:209], v[90:93]
	v_mfma_f32_16x16x32_bf16 v[90:93], v[138:141], v[202:205], v[90:93]
	v_mfma_f32_16x16x32_bf16 v[106:109], v[138:141], v[190:193], v[106:109]
	v_mfma_f32_16x16x32_bf16 v[106:109], v[142:145], v[194:197], v[106:109]
	v_mfma_f32_16x16x32_bf16 v[122:125], v[142:145], v[186:189], v[122:125]
	v_mfma_f32_16x16x32_bf16 v[122:125], v[138:141], v[182:185], v[122:125]
	v_mfma_f32_16x16x32_bf16 v[126:129], v[146:149], v[182:185], v[126:129]
	v_mfma_f32_16x16x32_bf16 v[126:129], v[150:153], v[186:189], v[126:129]
	v_mfma_f32_16x16x32_bf16 v[102:105], v[150:153], v[194:197], v[102:105]
	v_mfma_f32_16x16x32_bf16 v[102:105], v[146:149], v[190:193], v[102:105]
	v_mfma_f32_16x16x32_bf16 v[86:89], v[146:149], v[202:205], v[86:89]
	v_mfma_f32_16x16x32_bf16 v[86:89], v[150:153], v[206:209], v[86:89]
	v_mfma_f32_16x16x32_bf16 v[70:73], v[150:153], v[214:217], v[70:73]
	v_mfma_f32_16x16x32_bf16 v[70:73], v[146:149], v[210:213], v[70:73]
	v_mfma_f32_16x16x32_bf16 v[66:69], v[174:177], v[210:213], v[66:69]
	v_mfma_f32_16x16x32_bf16 v[66:69], v[178:181], v[214:217], v[66:69]
	v_mfma_f32_16x16x32_bf16 v[82:85], v[178:181], v[206:209], v[82:85]
	v_mfma_f32_16x16x32_bf16 v[82:85], v[174:177], v[202:205], v[82:85]
	v_mfma_f32_16x16x32_bf16 v[98:101], v[174:177], v[190:193], v[98:101]
	v_mfma_f32_16x16x32_bf16 v[98:101], v[178:181], v[194:197], v[98:101]
	v_mfma_f32_16x16x32_bf16 v[114:117], v[178:181], v[186:189], v[114:117]
	v_mfma_f32_16x16x32_bf16 v[114:117], v[174:177], v[182:185], v[114:117]
	s_barrier
	s_add_i32 s50, s74, s41
	s_mov_b32 m0, s50
	ds_read_b128 v[182:185], v200 offset:16384
	ds_read_b128 v[186:189], v200 offset:17408
	ds_read_b128 v[190:193], v200 offset:18432
	ds_read_b128 v[194:197], v200 offset:19456
	ds_read_b128 v[202:205], v200 offset:20480
	ds_read_b128 v[206:209], v200 offset:21504
	ds_read_b128 v[210:213], v200 offset:22528
	ds_read_b128 v[214:217], v200 offset:23552
	global_load_lds_dwordx4 v156, s[54:55]
	s_add_i32 m0, s50, 0x2000
	s_add_u32 s50, s54, 0x20000
	v_lshl_add_u64 v[220:221], s[54:55], 0, v[160:161]
	s_addc_u32 s51, s55, 0
	s_add_i32 s78, s75, s41
	global_load_lds_dwordx4 v160, s[54:55]
	s_mov_b32 m0, s78
	s_nop 0
	global_load_lds_dwordx4 v156, s[50:51]
	s_add_i32 m0, s78, 0x2000
	s_nop 0
	global_load_lds_dwordx4 v160, s[50:51]
	s_mov_b32 m0, s59
	s_nop 0
	global_load_lds_dwordx4 v154, s[56:57]
	s_mov_b32 m0, s60
	s_nop 0
	global_load_lds_dwordx4 v158, s[56:57]
	s_waitcnt vmcnt(8)
	s_waitcnt lgkmcnt(0)
	s_barrier
	v_mfma_f32_16x16x32_bf16 v[62:65], v[130:133], v[182:185], v[62:65]
	v_mfma_f32_16x16x32_bf16 v[62:65], v[134:137], v[186:189], v[62:65]
	v_mfma_f32_16x16x32_bf16 v[46:49], v[134:137], v[194:197], v[46:49]
	v_mfma_f32_16x16x32_bf16 v[46:49], v[130:133], v[190:193], v[46:49]
	v_mfma_f32_16x16x32_bf16 v[30:33], v[130:133], v[202:205], v[30:33]
	v_mfma_f32_16x16x32_bf16 v[30:33], v[134:137], v[206:209], v[30:33]
	v_mfma_f32_16x16x32_bf16 v[14:17], v[134:137], v[214:217], v[14:17]
	v_mfma_f32_16x16x32_bf16 v[14:17], v[130:133], v[210:213], v[14:17]
	v_mfma_f32_16x16x32_bf16 v[10:13], v[138:141], v[210:213], v[10:13]
	v_mfma_f32_16x16x32_bf16 v[10:13], v[142:145], v[214:217], v[10:13]
	v_mfma_f32_16x16x32_bf16 v[26:29], v[142:145], v[206:209], v[26:29]
	v_mfma_f32_16x16x32_bf16 v[26:29], v[138:141], v[202:205], v[26:29]
	v_mfma_f32_16x16x32_bf16 v[42:45], v[138:141], v[190:193], v[42:45]
	v_mfma_f32_16x16x32_bf16 v[42:45], v[142:145], v[194:197], v[42:45]
	v_mfma_f32_16x16x32_bf16 v[58:61], v[142:145], v[186:189], v[58:61]
	v_mfma_f32_16x16x32_bf16 v[58:61], v[138:141], v[182:185], v[58:61]
	v_mfma_f32_16x16x32_bf16 v[54:57], v[146:149], v[182:185], v[54:57]
	v_mfma_f32_16x16x32_bf16 v[54:57], v[150:153], v[186:189], v[54:57]
	v_mfma_f32_16x16x32_bf16 v[38:41], v[150:153], v[194:197], v[38:41]
	v_mfma_f32_16x16x32_bf16 v[38:41], v[146:149], v[190:193], v[38:41]
	v_mfma_f32_16x16x32_bf16 v[22:25], v[146:149], v[202:205], v[22:25]
	v_mfma_f32_16x16x32_bf16 v[22:25], v[150:153], v[206:209], v[22:25]
	v_mfma_f32_16x16x32_bf16 v[6:9], v[150:153], v[214:217], v[6:9]
	v_mfma_f32_16x16x32_bf16 v[6:9], v[146:149], v[210:213], v[6:9]
	v_mfma_f32_16x16x32_bf16 v[2:5], v[174:177], v[210:213], v[2:5]
	v_mfma_f32_16x16x32_bf16 v[2:5], v[178:181], v[214:217], v[2:5]
	v_mfma_f32_16x16x32_bf16 v[18:21], v[178:181], v[206:209], v[18:21]
	v_mfma_f32_16x16x32_bf16 v[18:21], v[174:177], v[202:205], v[18:21]
	v_mfma_f32_16x16x32_bf16 v[34:37], v[174:177], v[190:193], v[34:37]
	v_mfma_f32_16x16x32_bf16 v[34:37], v[178:181], v[194:197], v[34:37]
	v_mfma_f32_16x16x32_bf16 v[50:53], v[178:181], v[186:189], v[50:53]
	v_mfma_f32_16x16x32_bf16 v[50:53], v[174:177], v[182:185], v[50:53]
	s_barrier
	s_add_i32 s78, 0, 0x18000
	s_add_i32 s79, 0, 0x1c000
	v_add_u32_e32 v142, s78, v199
	v_add_u32_e32 v162, s79, v199
	ds_read_b128 v[130:133], v142
	ds_read_b128 v[134:137], v142 offset:1024
	ds_read_b128 v[138:141], v142 offset:2048
	ds_read_b128 v[142:145], v142 offset:3072
	ds_read_b128 v[146:149], v162
	ds_read_b128 v[150:153], v162 offset:1024
	ds_read_b128 v[174:177], v162 offset:2048
	ds_read_b128 v[178:181], v162 offset:3072
	s_add_u32 s50, s56, 0x1000
	s_addc_u32 s51, s57, 0
	s_mov_b32 m0, s61
	ds_read_b128 v[182:185], v200 offset:32768
	ds_read_b128 v[186:189], v200 offset:33792
	ds_read_b128 v[190:193], v200 offset:34816
	ds_read_b128 v[194:197], v200 offset:35840
	ds_read_b128 v[202:205], v200 offset:36864
	ds_read_b128 v[206:209], v200 offset:37888
	ds_read_b128 v[210:213], v200 offset:38912
	ds_read_b128 v[214:217], v200 offset:39936
	global_load_lds_dwordx4 v154, s[50:51]
	s_mov_b32 m0, s62
	s_nop 0
	global_load_lds_dwordx4 v158, s[50:51]
	s_waitcnt vmcnt(8)
	s_waitcnt lgkmcnt(0)
	s_barrier
	v_mfma_f32_16x16x32_bf16 v[118:121], v[130:133], v[182:185], v[118:121]
	v_mfma_f32_16x16x32_bf16 v[118:121], v[134:137], v[186:189], v[118:121]
	v_mfma_f32_16x16x32_bf16 v[110:113], v[134:137], v[194:197], v[110:113]
	v_mfma_f32_16x16x32_bf16 v[110:113], v[130:133], v[190:193], v[110:113]
	v_mfma_f32_16x16x32_bf16 v[94:97], v[130:133], v[202:205], v[94:97]
	v_mfma_f32_16x16x32_bf16 v[94:97], v[134:137], v[206:209], v[94:97]
	v_mfma_f32_16x16x32_bf16 v[78:81], v[134:137], v[214:217], v[78:81]
	v_mfma_f32_16x16x32_bf16 v[78:81], v[130:133], v[210:213], v[78:81]
	v_mfma_f32_16x16x32_bf16 v[74:77], v[138:141], v[210:213], v[74:77]
	v_mfma_f32_16x16x32_bf16 v[74:77], v[142:145], v[214:217], v[74:77]
	v_mfma_f32_16x16x32_bf16 v[90:93], v[142:145], v[206:209], v[90:93]
	v_mfma_f32_16x16x32_bf16 v[90:93], v[138:141], v[202:205], v[90:93]
	v_mfma_f32_16x16x32_bf16 v[106:109], v[138:141], v[190:193], v[106:109]
	v_mfma_f32_16x16x32_bf16 v[106:109], v[142:145], v[194:197], v[106:109]
	v_mfma_f32_16x16x32_bf16 v[122:125], v[142:145], v[186:189], v[122:125]
	v_mfma_f32_16x16x32_bf16 v[122:125], v[138:141], v[182:185], v[122:125]
	v_mfma_f32_16x16x32_bf16 v[126:129], v[146:149], v[182:185], v[126:129]
	v_mfma_f32_16x16x32_bf16 v[126:129], v[150:153], v[186:189], v[126:129]
	v_mfma_f32_16x16x32_bf16 v[102:105], v[150:153], v[194:197], v[102:105]
	v_mfma_f32_16x16x32_bf16 v[102:105], v[146:149], v[190:193], v[102:105]
	v_mfma_f32_16x16x32_bf16 v[86:89], v[146:149], v[202:205], v[86:89]
	v_mfma_f32_16x16x32_bf16 v[86:89], v[150:153], v[206:209], v[86:89]
	v_mfma_f32_16x16x32_bf16 v[70:73], v[150:153], v[214:217], v[70:73]
	v_mfma_f32_16x16x32_bf16 v[70:73], v[146:149], v[210:213], v[70:73]
	v_mfma_f32_16x16x32_bf16 v[66:69], v[174:177], v[210:213], v[66:69]
	v_mfma_f32_16x16x32_bf16 v[66:69], v[178:181], v[214:217], v[66:69]
	v_mfma_f32_16x16x32_bf16 v[82:85], v[178:181], v[206:209], v[82:85]
	v_mfma_f32_16x16x32_bf16 v[82:85], v[174:177], v[202:205], v[82:85]
	v_mfma_f32_16x16x32_bf16 v[98:101], v[174:177], v[190:193], v[98:101]
	v_mfma_f32_16x16x32_bf16 v[98:101], v[178:181], v[194:197], v[98:101]
	v_mfma_f32_16x16x32_bf16 v[114:117], v[178:181], v[186:189], v[114:117]
	v_mfma_f32_16x16x32_bf16 v[114:117], v[174:177], v[182:185], v[114:117]
	s_barrier
	s_add_i32 s50, s78, s41
	s_mov_b32 m0, s50
	ds_read_b128 v[182:185], v200 offset:49152
	ds_read_b128 v[186:189], v200 offset:50176
	ds_read_b128 v[190:193], v200 offset:51200
	ds_read_b128 v[194:197], v200 offset:52224
	ds_read_b128 v[202:205], v200 offset:53248
	ds_read_b128 v[206:209], v200 offset:54272
	ds_read_b128 v[210:213], v200 offset:55296
	ds_read_b128 v[214:217], v200 offset:56320
	s_add_u32 s98, s54, s14
	s_addc_u32 s99, s55, s15
	global_load_lds_dwordx4 v156, s[98:99]
	s_add_i32 m0, s50, 0x2000
	s_add_u32 s50, s54, 0x20080
	v_lshl_add_u64 v[218:219], v[220:221], 0, s[14:15]
	s_addc_u32 s51, s55, 0
	s_add_i32 s54, s79, s41
	global_load_lds_dwordx4 v[218:219], off
	s_mov_b32 m0, s54
	s_nop 0
	global_load_lds_dwordx4 v156, s[50:51]
	s_add_i32 m0, s54, 0x2000
	s_nop 0
	global_load_lds_dwordx4 v160, s[50:51]
	s_mov_b32 m0, s69
	s_nop 0
	global_load_lds_dwordx4 v154, s[52:53]
	s_mov_b32 m0, s70
	s_nop 0
	global_load_lds_dwordx4 v158, s[52:53]
	s_waitcnt vmcnt(8)
	s_waitcnt lgkmcnt(0)
	s_barrier
	v_mfma_f32_16x16x32_bf16 v[62:65], v[130:133], v[182:185], v[62:65]
	v_mfma_f32_16x16x32_bf16 v[62:65], v[134:137], v[186:189], v[62:65]
	v_mfma_f32_16x16x32_bf16 v[46:49], v[134:137], v[194:197], v[46:49]
	v_mfma_f32_16x16x32_bf16 v[46:49], v[130:133], v[190:193], v[46:49]
	v_mfma_f32_16x16x32_bf16 v[30:33], v[130:133], v[202:205], v[30:33]
	v_mfma_f32_16x16x32_bf16 v[30:33], v[134:137], v[206:209], v[30:33]
	v_mfma_f32_16x16x32_bf16 v[14:17], v[134:137], v[214:217], v[14:17]
	v_mfma_f32_16x16x32_bf16 v[14:17], v[130:133], v[210:213], v[14:17]
	v_mfma_f32_16x16x32_bf16 v[10:13], v[138:141], v[210:213], v[10:13]
	v_mfma_f32_16x16x32_bf16 v[10:13], v[142:145], v[214:217], v[10:13]
	v_mfma_f32_16x16x32_bf16 v[26:29], v[142:145], v[206:209], v[26:29]
	v_mfma_f32_16x16x32_bf16 v[26:29], v[138:141], v[202:205], v[26:29]
	v_mfma_f32_16x16x32_bf16 v[42:45], v[138:141], v[190:193], v[42:45]
	v_mfma_f32_16x16x32_bf16 v[42:45], v[142:145], v[194:197], v[42:45]
	v_mfma_f32_16x16x32_bf16 v[58:61], v[142:145], v[186:189], v[58:61]
	v_mfma_f32_16x16x32_bf16 v[58:61], v[138:141], v[182:185], v[58:61]
	v_mfma_f32_16x16x32_bf16 v[54:57], v[146:149], v[182:185], v[54:57]
	v_mfma_f32_16x16x32_bf16 v[54:57], v[150:153], v[186:189], v[54:57]
	v_mfma_f32_16x16x32_bf16 v[38:41], v[150:153], v[194:197], v[38:41]
	v_mfma_f32_16x16x32_bf16 v[38:41], v[146:149], v[190:193], v[38:41]
	v_mfma_f32_16x16x32_bf16 v[22:25], v[146:149], v[202:205], v[22:25]
	v_mfma_f32_16x16x32_bf16 v[22:25], v[150:153], v[206:209], v[22:25]
	v_mfma_f32_16x16x32_bf16 v[6:9], v[150:153], v[214:217], v[6:9]
	v_mfma_f32_16x16x32_bf16 v[6:9], v[146:149], v[210:213], v[6:9]
	v_mfma_f32_16x16x32_bf16 v[2:5], v[174:177], v[210:213], v[2:5]
	v_mfma_f32_16x16x32_bf16 v[2:5], v[178:181], v[214:217], v[2:5]
	v_mfma_f32_16x16x32_bf16 v[18:21], v[178:181], v[206:209], v[18:21]
	v_mfma_f32_16x16x32_bf16 v[18:21], v[174:177], v[202:205], v[18:21]
	v_mfma_f32_16x16x32_bf16 v[34:37], v[174:177], v[190:193], v[34:37]
	v_mfma_f32_16x16x32_bf16 v[34:37], v[178:181], v[194:197], v[34:37]
	v_mfma_f32_16x16x32_bf16 v[50:53], v[178:181], v[186:189], v[50:53]
	v_mfma_f32_16x16x32_bf16 v[50:53], v[174:177], v[182:185], v[50:53]
	s_barrier
	s_add_u32 s23, s23, 0x100
	s_addc_u32 s25, s25, 0
	s_add_u32 s34, s34, 0x800000
	s_addc_u32 s35, s35, 0
	s_cmp_ge_i32 s31, s67
	s_mov_b32 s52, s31
	s_cbranch_scc0 .LBB0_599

.LBB0_740:
	v_add_u32_e32 v144, s88, v188
	v_add_u32_e32 v160, s89, v188
	ds_read_b128 v[132:135], v144
	ds_read_b128 v[136:139], v144 offset:1024
	ds_read_b128 v[140:143], v144 offset:2048
	ds_read_b128 v[144:147], v144 offset:3072
	ds_read_b128 v[148:151], v160
	ds_read_b128 v[152:155], v160 offset:1024
	ds_read_b128 v[156:159], v160 offset:2048
	ds_read_b128 v[184:187], v160 offset:3072
	s_add_i32 s92, s55, 2
	s_add_u32 s50, s60, 0x3fc000
	s_addc_u32 s51, s61, 0
	s_cmp_eq_u32 s87, s55
	s_cselect_b32 s70, s64, s50
	s_cselect_b32 s71, s65, s51
	s_cselect_b32 s69, s67, s53
	s_cselect_b32 s68, s66, s13
	s_add_u32 s62, s70, 0x400000
	s_addc_u32 s63, s71, 0
	s_add_i32 m0, s77, 0xc000
	ds_read_b128 v[192:195], v189
	ds_read_b128 v[196:199], v189 offset:1024
	ds_read_b128 v[200:203], v189 offset:2048
	ds_read_b128 v[204:207], v189 offset:3072
	ds_read_b128 v[208:211], v189 offset:4096
	ds_read_b128 v[212:215], v189 offset:5120
	ds_read_b128 v[216:219], v189 offset:6144
	ds_read_b128 v[220:223], v189 offset:7168
	global_load_lds_dwordx4 v176, s[60:61]
	s_add_i32 m0, s77, 0xe000
	s_nop 0
	global_load_lds_dwordx4 v178, s[60:61]
	s_waitcnt vmcnt(8)
	s_waitcnt lgkmcnt(0)
	s_barrier
	v_mfma_f32_16x16x32_bf16 v[30:33], v[132:135], v[192:195], v[30:33]
	v_mfma_f32_16x16x32_bf16 v[30:33], v[136:139], v[196:199], v[30:33]
	v_mfma_f32_16x16x32_bf16 v[86:89], v[136:139], v[204:207], v[86:89]
	v_mfma_f32_16x16x32_bf16 v[86:89], v[132:135], v[200:203], v[86:89]
	v_mfma_f32_16x16x32_bf16 v[94:97], v[132:135], v[208:211], v[94:97]
	v_mfma_f32_16x16x32_bf16 v[94:97], v[136:139], v[212:215], v[94:97]
	v_mfma_f32_16x16x32_bf16 v[90:93], v[136:139], v[220:223], v[90:93]
	v_mfma_f32_16x16x32_bf16 v[90:93], v[132:135], v[216:219], v[90:93]
	v_mfma_f32_16x16x32_bf16 v[78:81], v[140:143], v[216:219], v[78:81]
	v_mfma_f32_16x16x32_bf16 v[78:81], v[144:147], v[220:223], v[78:81]
	v_mfma_f32_16x16x32_bf16 v[82:85], v[144:147], v[212:215], v[82:85]
	v_mfma_f32_16x16x32_bf16 v[82:85], v[140:143], v[208:211], v[82:85]
	v_mfma_f32_16x16x32_bf16 v[66:69], v[140:143], v[200:203], v[66:69]
	v_mfma_f32_16x16x32_bf16 v[66:69], v[144:147], v[204:207], v[66:69]
	v_mfma_f32_16x16x32_bf16 v[26:29], v[144:147], v[196:199], v[26:29]
	v_mfma_f32_16x16x32_bf16 v[26:29], v[140:143], v[192:195], v[26:29]
	v_mfma_f32_16x16x32_bf16 v[50:53], v[148:151], v[192:195], v[50:53]
	v_mfma_f32_16x16x32_bf16 v[50:53], v[152:155], v[196:199], v[50:53]
	v_mfma_f32_16x16x32_bf16 v[14:17], v[152:155], v[204:207], v[14:17]
	v_mfma_f32_16x16x32_bf16 v[14:17], v[148:151], v[200:203], v[14:17]
	v_mfma_f32_16x16x32_bf16 v[22:25], v[148:151], v[208:211], v[22:25]
	v_mfma_f32_16x16x32_bf16 v[22:25], v[152:155], v[212:215], v[22:25]
	v_mfma_f32_16x16x32_bf16 v[18:21], v[152:155], v[220:223], v[18:21]
	v_mfma_f32_16x16x32_bf16 v[18:21], v[148:151], v[216:219], v[18:21]
	v_mfma_f32_16x16x32_bf16 v[6:9], v[156:159], v[216:219], v[6:9]
	v_mfma_f32_16x16x32_bf16 v[6:9], v[184:187], v[220:223], v[6:9]
	v_mfma_f32_16x16x32_bf16 v[10:13], v[184:187], v[212:215], v[10:13]
	v_mfma_f32_16x16x32_bf16 v[10:13], v[156:159], v[208:211], v[10:13]
	v_mfma_f32_16x16x32_bf16 v[2:5], v[156:159], v[200:203], v[2:5]
	v_mfma_f32_16x16x32_bf16 v[2:5], v[184:187], v[204:207], v[2:5]
	v_mfma_f32_16x16x32_bf16 v[42:45], v[184:187], v[196:199], v[42:45]
	v_mfma_f32_16x16x32_bf16 v[42:45], v[156:159], v[192:195], v[42:45]
	s_barrier
	s_add_i32 s50, s88, s76
	s_mov_b32 m0, s50
	ds_read_b128 v[192:195], v189 offset:16384
	ds_read_b128 v[196:199], v189 offset:17408
	ds_read_b128 v[200:203], v189 offset:18432
	ds_read_b128 v[204:207], v189 offset:19456
	ds_read_b128 v[208:211], v189 offset:20480
	ds_read_b128 v[212:215], v189 offset:21504
	ds_read_b128 v[216:219], v189 offset:22528
	ds_read_b128 v[220:223], v189 offset:23552
	global_load_lds_dwordx4 v164, s[68:69]
	s_add_i32 m0, s50, 0x2000
	s_add_u32 s50, s68, 0x10000
	s_addc_u32 s51, s69, 0
	s_add_i32 s55, s89, s76
	global_load_lds_dwordx4 v168, s[68:69]
	s_mov_b32 m0, s55
	s_nop 0
	global_load_lds_dwordx4 v164, s[50:51]
	s_add_i32 m0, s55, 0x2000
	s_nop 0
	global_load_lds_dwordx4 v168, s[50:51]
	s_mov_b32 m0, s77
	s_nop 0
	global_load_lds_dwordx4 v162, s[70:71]
	s_mov_b32 m0, s78
	s_nop 0
	global_load_lds_dwordx4 v166, s[70:71]
	s_waitcnt vmcnt(8)
	s_waitcnt lgkmcnt(0)
	s_barrier
	v_mfma_f32_16x16x32_bf16 v[118:121], v[132:135], v[192:195], v[118:121]
	v_mfma_f32_16x16x32_bf16 v[118:121], v[136:139], v[196:199], v[118:121]
	v_mfma_f32_16x16x32_bf16 v[114:117], v[136:139], v[204:207], v[114:117]
	v_mfma_f32_16x16x32_bf16 v[114:117], v[132:135], v[200:203], v[114:117]
	v_mfma_f32_16x16x32_bf16 v[126:129], v[132:135], v[208:211], v[126:129]
	v_mfma_f32_16x16x32_bf16 v[126:129], v[136:139], v[212:215], v[126:129]
	v_mfma_f32_16x16x32_bf16 v[122:125], v[136:139], v[220:223], v[122:125]
	v_mfma_f32_16x16x32_bf16 v[122:125], v[132:135], v[216:219], v[122:125]
	v_mfma_f32_16x16x32_bf16 v[106:109], v[140:143], v[216:219], v[106:109]
	v_mfma_f32_16x16x32_bf16 v[106:109], v[144:147], v[220:223], v[106:109]
	v_mfma_f32_16x16x32_bf16 v[110:113], v[144:147], v[212:215], v[110:113]
	v_mfma_f32_16x16x32_bf16 v[110:113], v[140:143], v[208:211], v[110:113]
	v_mfma_f32_16x16x32_bf16 v[98:101], v[140:143], v[200:203], v[98:101]
	v_mfma_f32_16x16x32_bf16 v[98:101], v[144:147], v[204:207], v[98:101]
	v_mfma_f32_16x16x32_bf16 v[102:105], v[144:147], v[196:199], v[102:105]
	v_mfma_f32_16x16x32_bf16 v[102:105], v[140:143], v[192:195], v[102:105]
	v_mfma_f32_16x16x32_bf16 v[62:65], v[148:151], v[192:195], v[62:65]
	v_mfma_f32_16x16x32_bf16 v[62:65], v[152:155], v[196:199], v[62:65]
	v_mfma_f32_16x16x32_bf16 v[58:61], v[152:155], v[204:207], v[58:61]
	v_mfma_f32_16x16x32_bf16 v[58:61], v[148:151], v[200:203], v[58:61]
	v_mfma_f32_16x16x32_bf16 v[74:77], v[148:151], v[208:211], v[74:77]
	v_mfma_f32_16x16x32_bf16 v[74:77], v[152:155], v[212:215], v[74:77]
	v_mfma_f32_16x16x32_bf16 v[70:73], v[152:155], v[220:223], v[70:73]
	v_mfma_f32_16x16x32_bf16 v[70:73], v[148:151], v[216:219], v[70:73]
	v_mfma_f32_16x16x32_bf16 v[46:49], v[156:159], v[216:219], v[46:49]
	v_mfma_f32_16x16x32_bf16 v[46:49], v[184:187], v[220:223], v[46:49]
	v_mfma_f32_16x16x32_bf16 v[54:57], v[184:187], v[212:215], v[54:57]
	v_mfma_f32_16x16x32_bf16 v[54:57], v[156:159], v[208:211], v[54:57]
	v_mfma_f32_16x16x32_bf16 v[34:37], v[156:159], v[200:203], v[34:37]
	v_mfma_f32_16x16x32_bf16 v[34:37], v[184:187], v[204:207], v[34:37]
	v_mfma_f32_16x16x32_bf16 v[38:41], v[184:187], v[196:199], v[38:41]
	v_mfma_f32_16x16x32_bf16 v[38:41], v[156:159], v[192:195], v[38:41]
	s_barrier
	s_add_i32 s55, 0, 0x18000
	s_add_i32 s93, 0, 0x1c000
	v_add_u32_e32 v144, s55, v188
	v_add_u32_e32 v184, s93, v188
	ds_read_b128 v[132:135], v144
	ds_read_b128 v[136:139], v144 offset:1024
	ds_read_b128 v[140:143], v144 offset:2048
	ds_read_b128 v[144:147], v144 offset:3072
	ds_read_b128 v[148:151], v184
	ds_read_b128 v[152:155], v184 offset:1024
	ds_read_b128 v[156:159], v184 offset:2048
	ds_read_b128 v[184:187], v184 offset:3072
	s_add_u32 s50, s70, 0x4000
	s_addc_u32 s51, s71, 0
	s_mov_b32 m0, s79
	ds_read_b128 v[192:195], v189 offset:32768
	ds_read_b128 v[196:199], v189 offset:33792
	ds_read_b128 v[200:203], v189 offset:34816
	ds_read_b128 v[204:207], v189 offset:35840
	ds_read_b128 v[208:211], v189 offset:36864
	ds_read_b128 v[212:215], v189 offset:37888
	ds_read_b128 v[216:219], v189 offset:38912
	ds_read_b128 v[220:223], v189 offset:39936
	global_load_lds_dwordx4 v162, s[50:51]
	s_mov_b32 m0, s80
	s_nop 0
	global_load_lds_dwordx4 v166, s[50:51]
	s_waitcnt vmcnt(8)
	s_waitcnt lgkmcnt(0)
	s_barrier
	v_mfma_f32_16x16x32_bf16 v[30:33], v[132:135], v[192:195], v[30:33]
	v_mfma_f32_16x16x32_bf16 v[30:33], v[136:139], v[196:199], v[30:33]
	v_mfma_f32_16x16x32_bf16 v[86:89], v[136:139], v[204:207], v[86:89]
	v_mfma_f32_16x16x32_bf16 v[86:89], v[132:135], v[200:203], v[86:89]
	v_mfma_f32_16x16x32_bf16 v[94:97], v[132:135], v[208:211], v[94:97]
	v_mfma_f32_16x16x32_bf16 v[94:97], v[136:139], v[212:215], v[94:97]
	v_mfma_f32_16x16x32_bf16 v[90:93], v[136:139], v[220:223], v[90:93]
	v_mfma_f32_16x16x32_bf16 v[90:93], v[132:135], v[216:219], v[90:93]
	v_mfma_f32_16x16x32_bf16 v[78:81], v[140:143], v[216:219], v[78:81]
	v_mfma_f32_16x16x32_bf16 v[78:81], v[144:147], v[220:223], v[78:81]
	v_mfma_f32_16x16x32_bf16 v[82:85], v[144:147], v[212:215], v[82:85]
	v_mfma_f32_16x16x32_bf16 v[82:85], v[140:143], v[208:211], v[82:85]
	v_mfma_f32_16x16x32_bf16 v[66:69], v[140:143], v[200:203], v[66:69]
	v_mfma_f32_16x16x32_bf16 v[66:69], v[144:147], v[204:207], v[66:69]
	v_mfma_f32_16x16x32_bf16 v[26:29], v[144:147], v[196:199], v[26:29]
	v_mfma_f32_16x16x32_bf16 v[26:29], v[140:143], v[192:195], v[26:29]
	v_mfma_f32_16x16x32_bf16 v[50:53], v[148:151], v[192:195], v[50:53]
	v_mfma_f32_16x16x32_bf16 v[50:53], v[152:155], v[196:199], v[50:53]
	v_mfma_f32_16x16x32_bf16 v[14:17], v[152:155], v[204:207], v[14:17]
	v_mfma_f32_16x16x32_bf16 v[14:17], v[148:151], v[200:203], v[14:17]
	v_mfma_f32_16x16x32_bf16 v[22:25], v[148:151], v[208:211], v[22:25]
	v_mfma_f32_16x16x32_bf16 v[22:25], v[152:155], v[212:215], v[22:25]
	v_mfma_f32_16x16x32_bf16 v[18:21], v[152:155], v[220:223], v[18:21]
	v_mfma_f32_16x16x32_bf16 v[18:21], v[148:151], v[216:219], v[18:21]
	v_mfma_f32_16x16x32_bf16 v[6:9], v[156:159], v[216:219], v[6:9]
	v_mfma_f32_16x16x32_bf16 v[6:9], v[184:187], v[220:223], v[6:9]
	v_mfma_f32_16x16x32_bf16 v[10:13], v[184:187], v[212:215], v[10:13]
	v_mfma_f32_16x16x32_bf16 v[10:13], v[156:159], v[208:211], v[10:13]
	v_mfma_f32_16x16x32_bf16 v[2:5], v[156:159], v[200:203], v[2:5]
	v_mfma_f32_16x16x32_bf16 v[2:5], v[184:187], v[204:207], v[2:5]
	v_mfma_f32_16x16x32_bf16 v[42:45], v[184:187], v[196:199], v[42:45]
	v_mfma_f32_16x16x32_bf16 v[42:45], v[156:159], v[192:195], v[42:45]
	s_barrier
	s_add_i32 s50, s55, s76
	s_mov_b32 m0, s50
	ds_read_b128 v[192:195], v189 offset:49152
	ds_read_b128 v[196:199], v189 offset:50176
	ds_read_b128 v[200:203], v189 offset:51200
	ds_read_b128 v[204:207], v189 offset:52224
	ds_read_b128 v[208:211], v189 offset:53248
	ds_read_b128 v[212:215], v189 offset:54272
	ds_read_b128 v[216:219], v189 offset:55296
	ds_read_b128 v[220:223], v189 offset:56320
	s_add_u32 s98, s68, s14
	s_addc_u32 s99, s69, s15
	global_load_lds_dwordx4 v164, s[98:99]
	s_add_i32 m0, s50, 0x2000
	s_add_u32 s50, s68, 0x10080
	s_addc_u32 s51, s69, 0
	s_add_i32 s55, s93, s76
	s_add_u32 s100, s68, s14
	s_addc_u32 s101, s69, s15
	global_load_lds_dwordx4 v168, s[100:101]
	s_mov_b32 m0, s55
	s_nop 0
	global_load_lds_dwordx4 v164, s[50:51]
	s_add_i32 m0, s55, 0x2000
	s_nop 0
	global_load_lds_dwordx4 v168, s[50:51]
	s_mov_b32 m0, s84
	s_nop 0
	global_load_lds_dwordx4 v162, s[62:63]
	s_mov_b32 m0, s85
	s_nop 0
	global_load_lds_dwordx4 v166, s[62:63]
	s_waitcnt vmcnt(8)
	s_waitcnt lgkmcnt(0)
	s_barrier
	v_mfma_f32_16x16x32_bf16 v[118:121], v[132:135], v[192:195], v[118:121]
	v_mfma_f32_16x16x32_bf16 v[118:121], v[136:139], v[196:199], v[118:121]
	v_mfma_f32_16x16x32_bf16 v[114:117], v[136:139], v[204:207], v[114:117]
	v_mfma_f32_16x16x32_bf16 v[114:117], v[132:135], v[200:203], v[114:117]
	v_mfma_f32_16x16x32_bf16 v[126:129], v[132:135], v[208:211], v[126:129]
	v_mfma_f32_16x16x32_bf16 v[126:129], v[136:139], v[212:215], v[126:129]
	v_mfma_f32_16x16x32_bf16 v[122:125], v[136:139], v[220:223], v[122:125]
	v_mfma_f32_16x16x32_bf16 v[122:125], v[132:135], v[216:219], v[122:125]
	v_mfma_f32_16x16x32_bf16 v[106:109], v[140:143], v[216:219], v[106:109]
	v_mfma_f32_16x16x32_bf16 v[106:109], v[144:147], v[220:223], v[106:109]
	v_mfma_f32_16x16x32_bf16 v[110:113], v[144:147], v[212:215], v[110:113]
	v_mfma_f32_16x16x32_bf16 v[110:113], v[140:143], v[208:211], v[110:113]
	v_mfma_f32_16x16x32_bf16 v[98:101], v[140:143], v[200:203], v[98:101]
	v_mfma_f32_16x16x32_bf16 v[98:101], v[144:147], v[204:207], v[98:101]
	v_mfma_f32_16x16x32_bf16 v[102:105], v[144:147], v[196:199], v[102:105]
	v_mfma_f32_16x16x32_bf16 v[102:105], v[140:143], v[192:195], v[102:105]
	v_mfma_f32_16x16x32_bf16 v[62:65], v[148:151], v[192:195], v[62:65]
	v_mfma_f32_16x16x32_bf16 v[62:65], v[152:155], v[196:199], v[62:65]
	v_mfma_f32_16x16x32_bf16 v[58:61], v[152:155], v[204:207], v[58:61]
	v_mfma_f32_16x16x32_bf16 v[58:61], v[148:151], v[200:203], v[58:61]
	v_mfma_f32_16x16x32_bf16 v[74:77], v[148:151], v[208:211], v[74:77]
	v_mfma_f32_16x16x32_bf16 v[74:77], v[152:155], v[212:215], v[74:77]
	v_mfma_f32_16x16x32_bf16 v[70:73], v[152:155], v[220:223], v[70:73]
	v_mfma_f32_16x16x32_bf16 v[70:73], v[148:151], v[216:219], v[70:73]
	v_mfma_f32_16x16x32_bf16 v[46:49], v[156:159], v[216:219], v[46:49]
	v_mfma_f32_16x16x32_bf16 v[46:49], v[184:187], v[220:223], v[46:49]
	v_mfma_f32_16x16x32_bf16 v[54:57], v[184:187], v[212:215], v[54:57]
	v_mfma_f32_16x16x32_bf16 v[54:57], v[156:159], v[208:211], v[54:57]
	v_mfma_f32_16x16x32_bf16 v[34:37], v[156:159], v[200:203], v[34:37]
	v_mfma_f32_16x16x32_bf16 v[34:37], v[184:187], v[204:207], v[34:37]
	v_mfma_f32_16x16x32_bf16 v[38:41], v[184:187], v[196:199], v[38:41]
	v_mfma_f32_16x16x32_bf16 v[38:41], v[156:159], v[192:195], v[38:41]
	s_barrier
	s_add_u32 s13, s13, 0x100
	s_addc_u32 s53, s53, 0
	s_add_u32 s60, s60, 0x800000
	s_addc_u32 s61, s61, 0
	s_cmp_ge_i32 s92, s83
	s_cbranch_scc0 .LBB0_738

.LBB0_1009:
	v_add_u32_e32 v0, s64, v187
	ds_read_b128 v[130:133], v0
	ds_read_b128 v[134:137], v0 offset:1024
	ds_read_b128 v[138:141], v0 offset:2048
	ds_read_b128 v[142:145], v0 offset:3072
	v_add_u32_e32 v0, s65, v187
	ds_read_b128 v[146:149], v0
	ds_read_b128 v[150:153], v0 offset:1024
	ds_read_b128 v[178:181], v0 offset:2048
	ds_read_b128 v[182:185], v0 offset:3072
	s_add_i32 s35, s42, 2
	s_add_u32 s43, s36, 0x3fc000
	s_addc_u32 s44, s37, 0
	s_cmp_eq_u32 s61, s42
	s_cselect_b32 s46, s28, s43
	s_cselect_b32 s47, s29, s44
	s_cselect_b32 s44, s30, s11
	s_cselect_b32 s45, s31, s27
	s_add_u32 s42, s46, 0x400000
	s_addc_u32 s43, s47, 0
	s_add_i32 m0, s51, 0xc000
	ds_read_b128 v[220:223], v215
	ds_read_b128 v[224:227], v215 offset:1024
	ds_read_b128 v[228:231], v215 offset:2048
	ds_read_b128 v[232:235], v215 offset:3072
	ds_read_b128 v[236:239], v215 offset:4096
	ds_read_b128 v[240:243], v215 offset:5120
	ds_read_b128 v[244:247], v215 offset:6144
	ds_read_b128 v[248:251], v215 offset:7168
	global_load_lds_dwordx4 v168, s[36:37]
	s_add_i32 m0, s51, 0xe000
	s_nop 0
	global_load_lds_dwordx4 v170, s[36:37]
	s_waitcnt vmcnt(8)
	s_waitcnt lgkmcnt(0)
	s_barrier
	v_mfma_f32_16x16x32_bf16 v[114:117], v[130:133], v[220:223], v[114:117]
	v_mfma_f32_16x16x32_bf16 v[114:117], v[134:137], v[224:227], v[114:117]
	v_mfma_f32_16x16x32_bf16 v[110:113], v[134:137], v[232:235], v[110:113]
	v_mfma_f32_16x16x32_bf16 v[110:113], v[130:133], v[228:231], v[110:113]
	v_mfma_f32_16x16x32_bf16 v[94:97], v[130:133], v[236:239], v[94:97]
	v_mfma_f32_16x16x32_bf16 v[94:97], v[134:137], v[240:243], v[94:97]
	v_mfma_f32_16x16x32_bf16 v[78:81], v[134:137], v[248:251], v[78:81]
	v_mfma_f32_16x16x32_bf16 v[78:81], v[130:133], v[244:247], v[78:81]
	v_mfma_f32_16x16x32_bf16 v[70:73], v[138:141], v[244:247], v[70:73]
	v_mfma_f32_16x16x32_bf16 v[70:73], v[142:145], v[248:251], v[70:73]
	v_mfma_f32_16x16x32_bf16 v[86:89], v[142:145], v[240:243], v[86:89]
	v_mfma_f32_16x16x32_bf16 v[86:89], v[138:141], v[236:239], v[86:89]
	v_mfma_f32_16x16x32_bf16 v[102:105], v[138:141], v[228:231], v[102:105]
	v_mfma_f32_16x16x32_bf16 v[102:105], v[142:145], v[232:235], v[102:105]
	v_mfma_f32_16x16x32_bf16 v[118:121], v[142:145], v[224:227], v[118:121]
	v_mfma_f32_16x16x32_bf16 v[118:121], v[138:141], v[220:223], v[118:121]
	v_mfma_f32_16x16x32_bf16 v[126:129], v[146:149], v[220:223], v[126:129]
	v_mfma_f32_16x16x32_bf16 v[126:129], v[150:153], v[224:227], v[126:129]
	v_mfma_f32_16x16x32_bf16 v[106:109], v[150:153], v[232:235], v[106:109]
	v_mfma_f32_16x16x32_bf16 v[106:109], v[146:149], v[228:231], v[106:109]
	v_mfma_f32_16x16x32_bf16 v[90:93], v[146:149], v[236:239], v[90:93]
	v_mfma_f32_16x16x32_bf16 v[90:93], v[150:153], v[240:243], v[90:93]
	v_mfma_f32_16x16x32_bf16 v[74:77], v[150:153], v[248:251], v[74:77]
	v_mfma_f32_16x16x32_bf16 v[74:77], v[146:149], v[244:247], v[74:77]
	v_mfma_f32_16x16x32_bf16 v[66:69], v[178:181], v[244:247], v[66:69]
	v_mfma_f32_16x16x32_bf16 v[66:69], v[182:185], v[248:251], v[66:69]
	v_mfma_f32_16x16x32_bf16 v[82:85], v[182:185], v[240:243], v[82:85]
	v_mfma_f32_16x16x32_bf16 v[82:85], v[178:181], v[236:239], v[82:85]
	v_mfma_f32_16x16x32_bf16 v[98:101], v[178:181], v[228:231], v[98:101]
	v_mfma_f32_16x16x32_bf16 v[98:101], v[182:185], v[232:235], v[98:101]
	v_mfma_f32_16x16x32_bf16 v[122:125], v[182:185], v[224:227], v[122:125]
	v_mfma_f32_16x16x32_bf16 v[122:125], v[178:181], v[220:223], v[122:125]
	s_barrier
	s_add_i32 s69, s64, s49
	s_mov_b32 m0, s69
	ds_read_b128 v[220:223], v215 offset:16384
	ds_read_b128 v[224:227], v215 offset:17408
	ds_read_b128 v[228:231], v215 offset:18432
	ds_read_b128 v[232:235], v215 offset:19456
	ds_read_b128 v[236:239], v215 offset:20480
	ds_read_b128 v[240:243], v215 offset:21504
	ds_read_b128 v[244:247], v215 offset:22528
	ds_read_b128 v[248:251], v215 offset:23552
	global_load_lds_dwordx4 v156, s[44:45]
	s_add_i32 m0, s69, 0x2000
	s_add_u32 s70, s44, 0xb0000
	v_lshl_add_u64 v[172:173], s[44:45], 0, v[160:161]
	s_addc_u32 s71, s45, 0
	s_add_i32 s69, s65, s49
	global_load_lds_dwordx4 v160, s[44:45]
	s_mov_b32 m0, s69
	s_nop 0
	global_load_lds_dwordx4 v156, s[70:71]
	s_add_i32 m0, s69, 0x2000
	s_nop 0
	global_load_lds_dwordx4 v160, s[70:71]
	s_mov_b32 m0, s51
	s_nop 0
	global_load_lds_dwordx4 v154, s[46:47]
	s_mov_b32 m0, s52
	s_nop 0
	global_load_lds_dwordx4 v158, s[46:47]
	s_waitcnt vmcnt(8)
	s_waitcnt lgkmcnt(0)
	s_barrier
	v_mfma_f32_16x16x32_bf16 v[50:53], v[130:133], v[220:223], v[50:53]
	v_mfma_f32_16x16x32_bf16 v[50:53], v[134:137], v[224:227], v[50:53]
	v_mfma_f32_16x16x32_bf16 v[54:57], v[142:145], v[224:227], v[54:57]
	v_mfma_f32_16x16x32_bf16 v[54:57], v[138:141], v[220:223], v[54:57]
	v_mfma_f32_16x16x32_bf16 v[46:49], v[130:133], v[228:231], v[46:49]
	v_mfma_f32_16x16x32_bf16 v[46:49], v[134:137], v[232:235], v[46:49]
	v_mfma_f32_16x16x32_bf16 v[38:41], v[142:145], v[232:235], v[38:41]
	v_mfma_f32_16x16x32_bf16 v[38:41], v[138:141], v[228:231], v[38:41]
	v_mfma_f32_16x16x32_bf16 v[30:33], v[130:133], v[236:239], v[30:33]
	v_mfma_f32_16x16x32_bf16 v[30:33], v[134:137], v[240:243], v[30:33]
	v_mfma_f32_16x16x32_bf16 v[22:25], v[142:145], v[240:243], v[22:25]
	v_mfma_f32_16x16x32_bf16 v[22:25], v[138:141], v[236:239], v[22:25]
	v_mfma_f32_16x16x32_bf16 v[14:17], v[130:133], v[244:247], v[14:17]
	v_mfma_f32_16x16x32_bf16 v[14:17], v[134:137], v[248:251], v[14:17]
	v_mfma_f32_16x16x32_bf16 v[62:65], v[150:153], v[224:227], v[62:65]
	v_mfma_f32_16x16x32_bf16 v[62:65], v[146:149], v[220:223], v[62:65]
	v_mfma_f32_16x16x32_bf16 v[58:61], v[178:181], v[220:223], v[58:61]
	v_mfma_f32_16x16x32_bf16 v[58:61], v[182:185], v[224:227], v[58:61]
	v_mfma_f32_16x16x32_bf16 v[42:45], v[150:153], v[232:235], v[42:45]
	v_mfma_f32_16x16x32_bf16 v[42:45], v[146:149], v[228:231], v[42:45]
	v_mfma_f32_16x16x32_bf16 v[34:37], v[178:181], v[228:231], v[34:37]
	v_mfma_f32_16x16x32_bf16 v[34:37], v[182:185], v[232:235], v[34:37]
	v_mfma_f32_16x16x32_bf16 v[26:29], v[150:153], v[240:243], v[26:29]
	v_mfma_f32_16x16x32_bf16 v[26:29], v[146:149], v[236:239], v[26:29]
	v_mfma_f32_16x16x32_bf16 v[18:21], v[178:181], v[236:239], v[18:21]
	v_mfma_f32_16x16x32_bf16 v[18:21], v[182:185], v[240:243], v[18:21]
	v_mfma_f32_16x16x32_bf16 v[10:13], v[150:153], v[248:251], v[10:13]
	v_mfma_f32_16x16x32_bf16 v[10:13], v[146:149], v[244:247], v[10:13]
	v_mfma_f32_16x16x32_bf16 v[6:9], v[138:141], v[244:247], v[6:9]
	v_mfma_f32_16x16x32_bf16 v[6:9], v[142:145], v[248:251], v[6:9]
	v_mfma_f32_16x16x32_bf16 v[0:3], v[178:181], v[244:247], v[2:5]
	v_mfma_f32_16x16x32_bf16 v[0:3], v[182:185], v[248:251], v[0:3]
	s_barrier
	s_add_i32 s69, 0, 0x18000
	v_add_u32_e32 v4, s69, v187
	s_add_i32 s70, 0, 0x1c000
	ds_read_b128 v[130:133], v4
	ds_read_b128 v[134:137], v4 offset:1024
	ds_read_b128 v[138:141], v4 offset:2048
	ds_read_b128 v[142:145], v4 offset:3072
	v_add_u32_e32 v4, s70, v187
	ds_read_b128 v[146:149], v4
	ds_read_b128 v[150:153], v4 offset:1024
	ds_read_b128 v[178:181], v4 offset:2048
	ds_read_b128 v[182:185], v4 offset:3072
	s_add_u32 s46, s46, 0x4000
	s_addc_u32 s47, s47, 0
	s_mov_b32 m0, s53
	ds_read_b128 v[220:223], v215 offset:32768
	ds_read_b128 v[224:227], v215 offset:33792
	ds_read_b128 v[228:231], v215 offset:34816
	ds_read_b128 v[232:235], v215 offset:35840
	ds_read_b128 v[236:239], v215 offset:36864
	ds_read_b128 v[240:243], v215 offset:37888
	ds_read_b128 v[244:247], v215 offset:38912
	ds_read_b128 v[248:251], v215 offset:39936
	global_load_lds_dwordx4 v154, s[46:47]
	s_mov_b32 m0, s54
	s_nop 0
	global_load_lds_dwordx4 v158, s[46:47]
	s_waitcnt vmcnt(8)
	s_waitcnt lgkmcnt(0)
	s_barrier
	v_mfma_f32_16x16x32_bf16 v[114:117], v[130:133], v[220:223], v[114:117]
	v_mfma_f32_16x16x32_bf16 v[114:117], v[134:137], v[224:227], v[114:117]
	v_mfma_f32_16x16x32_bf16 v[110:113], v[134:137], v[232:235], v[110:113]
	v_mfma_f32_16x16x32_bf16 v[110:113], v[130:133], v[228:231], v[110:113]
	v_mfma_f32_16x16x32_bf16 v[94:97], v[130:133], v[236:239], v[94:97]
	v_mfma_f32_16x16x32_bf16 v[94:97], v[134:137], v[240:243], v[94:97]
	v_mfma_f32_16x16x32_bf16 v[78:81], v[134:137], v[248:251], v[78:81]
	v_mfma_f32_16x16x32_bf16 v[78:81], v[130:133], v[244:247], v[78:81]
	v_mfma_f32_16x16x32_bf16 v[70:73], v[138:141], v[244:247], v[70:73]
	v_mfma_f32_16x16x32_bf16 v[70:73], v[142:145], v[248:251], v[70:73]
	v_mfma_f32_16x16x32_bf16 v[86:89], v[142:145], v[240:243], v[86:89]
	v_mfma_f32_16x16x32_bf16 v[86:89], v[138:141], v[236:239], v[86:89]
	v_mfma_f32_16x16x32_bf16 v[102:105], v[138:141], v[228:231], v[102:105]
	v_mfma_f32_16x16x32_bf16 v[102:105], v[142:145], v[232:235], v[102:105]
	v_mfma_f32_16x16x32_bf16 v[118:121], v[142:145], v[224:227], v[118:121]
	v_mfma_f32_16x16x32_bf16 v[118:121], v[138:141], v[220:223], v[118:121]
	v_mfma_f32_16x16x32_bf16 v[126:129], v[146:149], v[220:223], v[126:129]
	v_mfma_f32_16x16x32_bf16 v[126:129], v[150:153], v[224:227], v[126:129]
	v_mfma_f32_16x16x32_bf16 v[106:109], v[150:153], v[232:235], v[106:109]
	v_mfma_f32_16x16x32_bf16 v[106:109], v[146:149], v[228:231], v[106:109]
	v_mfma_f32_16x16x32_bf16 v[90:93], v[146:149], v[236:239], v[90:93]
	v_mfma_f32_16x16x32_bf16 v[90:93], v[150:153], v[240:243], v[90:93]
	v_mfma_f32_16x16x32_bf16 v[74:77], v[150:153], v[248:251], v[74:77]
	v_mfma_f32_16x16x32_bf16 v[74:77], v[146:149], v[244:247], v[74:77]
	v_mfma_f32_16x16x32_bf16 v[66:69], v[178:181], v[244:247], v[66:69]
	v_mfma_f32_16x16x32_bf16 v[66:69], v[182:185], v[248:251], v[66:69]
	v_mfma_f32_16x16x32_bf16 v[82:85], v[182:185], v[240:243], v[82:85]
	v_mfma_f32_16x16x32_bf16 v[82:85], v[178:181], v[236:239], v[82:85]
	v_mfma_f32_16x16x32_bf16 v[98:101], v[178:181], v[228:231], v[98:101]
	v_mfma_f32_16x16x32_bf16 v[98:101], v[182:185], v[232:235], v[98:101]
	v_mfma_f32_16x16x32_bf16 v[122:125], v[182:185], v[224:227], v[122:125]
	v_mfma_f32_16x16x32_bf16 v[122:125], v[178:181], v[220:223], v[122:125]
	s_barrier
	s_add_i32 s46, s69, s49
	s_mov_b32 m0, s46
	ds_read_b128 v[220:223], v215 offset:49152
	ds_read_b128 v[224:227], v215 offset:50176
	ds_read_b128 v[228:231], v215 offset:51200
	ds_read_b128 v[232:235], v215 offset:52224
	ds_read_b128 v[236:239], v215 offset:53248
	ds_read_b128 v[240:243], v215 offset:54272
	ds_read_b128 v[244:247], v215 offset:55296
	ds_read_b128 v[248:251], v215 offset:56320
	s_add_u32 s98, s44, s18
	s_addc_u32 s99, s45, s19
	global_load_lds_dwordx4 v156, s[98:99]
	s_add_i32 m0, s46, 0x2000
	s_add_u32 s44, s44, 0xb0080
	v_lshl_add_u64 v[4:5], v[172:173], 0, s[18:19]
	s_addc_u32 s45, s45, 0
	s_add_i32 s46, s70, s49
	global_load_lds_dwordx4 v[4:5], off
	s_mov_b32 m0, s46
	s_nop 0
	global_load_lds_dwordx4 v156, s[44:45]
	s_add_i32 m0, s46, 0x2000
	s_nop 0
	global_load_lds_dwordx4 v160, s[44:45]
	s_mov_b32 m0, s59
	s_nop 0
	global_load_lds_dwordx4 v154, s[42:43]
	s_mov_b32 m0, s60
	s_nop 0
	global_load_lds_dwordx4 v158, s[42:43]
	s_waitcnt vmcnt(8)
	s_waitcnt lgkmcnt(0)
	s_barrier
	v_mfma_f32_16x16x32_bf16 v[50:53], v[130:133], v[220:223], v[50:53]
	v_mfma_f32_16x16x32_bf16 v[50:53], v[134:137], v[224:227], v[50:53]
	v_mfma_f32_16x16x32_bf16 v[54:57], v[142:145], v[224:227], v[54:57]
	v_mfma_f32_16x16x32_bf16 v[54:57], v[138:141], v[220:223], v[54:57]
	v_mfma_f32_16x16x32_bf16 v[46:49], v[130:133], v[228:231], v[46:49]
	v_mfma_f32_16x16x32_bf16 v[46:49], v[134:137], v[232:235], v[46:49]
	v_mfma_f32_16x16x32_bf16 v[38:41], v[142:145], v[232:235], v[38:41]
	v_mfma_f32_16x16x32_bf16 v[38:41], v[138:141], v[228:231], v[38:41]
	v_mfma_f32_16x16x32_bf16 v[30:33], v[130:133], v[236:239], v[30:33]
	v_mfma_f32_16x16x32_bf16 v[30:33], v[134:137], v[240:243], v[30:33]
	v_mfma_f32_16x16x32_bf16 v[22:25], v[142:145], v[240:243], v[22:25]
	v_mfma_f32_16x16x32_bf16 v[22:25], v[138:141], v[236:239], v[22:25]
	v_mfma_f32_16x16x32_bf16 v[14:17], v[130:133], v[244:247], v[14:17]
	v_mfma_f32_16x16x32_bf16 v[14:17], v[134:137], v[248:251], v[14:17]
	v_mfma_f32_16x16x32_bf16 v[62:65], v[150:153], v[224:227], v[62:65]
	v_mfma_f32_16x16x32_bf16 v[62:65], v[146:149], v[220:223], v[62:65]
	v_mfma_f32_16x16x32_bf16 v[58:61], v[178:181], v[220:223], v[58:61]
	v_mfma_f32_16x16x32_bf16 v[58:61], v[182:185], v[224:227], v[58:61]
	v_mfma_f32_16x16x32_bf16 v[42:45], v[150:153], v[232:235], v[42:45]
	v_mfma_f32_16x16x32_bf16 v[42:45], v[146:149], v[228:231], v[42:45]
	v_mfma_f32_16x16x32_bf16 v[34:37], v[178:181], v[228:231], v[34:37]
	v_mfma_f32_16x16x32_bf16 v[34:37], v[182:185], v[232:235], v[34:37]
	v_mfma_f32_16x16x32_bf16 v[26:29], v[150:153], v[240:243], v[26:29]
	v_mfma_f32_16x16x32_bf16 v[26:29], v[146:149], v[236:239], v[26:29]
	v_mfma_f32_16x16x32_bf16 v[18:21], v[178:181], v[236:239], v[18:21]
	v_mfma_f32_16x16x32_bf16 v[18:21], v[182:185], v[240:243], v[18:21]
	v_mfma_f32_16x16x32_bf16 v[10:13], v[150:153], v[248:251], v[10:13]
	v_mfma_f32_16x16x32_bf16 v[10:13], v[146:149], v[244:247], v[10:13]
	v_mfma_f32_16x16x32_bf16 v[4:7], v[138:141], v[244:247], v[6:9]
	v_mfma_f32_16x16x32_bf16 v[6:9], v[142:145], v[248:251], v[4:7]
	v_mfma_f32_16x16x32_bf16 v[0:3], v[178:181], v[244:247], v[0:3]
	v_mfma_f32_16x16x32_bf16 v[2:5], v[182:185], v[248:251], v[0:3]
	s_barrier
	s_add_u32 s11, s11, 0x100
	s_addc_u32 s27, s27, 0
	s_add_u32 s36, s36, 0x800000
	s_addc_u32 s37, s37, 0
	s_cmp_ge_i32 s35, s58
	s_mov_b32 s42, s35
	s_cbranch_scc0 .LBB0_1009
	v_mov_b64_e32 v[234:235], v[174:175]
	s_and_b64 vcc, exec, s[22:23]
	s_cbranch_vccnz .LBB0_980
	s_branch .LBB0_981
